# SwiGLU epilogue packed-f32 rewrite + FFN1-down epilogue loads batched + su-load hoist + v_mov_b64 acc zeroing
# speedup vs baseline: 1.0106x; 1.0106x over previous
.LBB0_283:
	s_ashr_i32 s25, s24, 31
	s_lshl_b64 s[26:27], s[24:25], 19
	s_add_u32 s26, s19, s26
	s_addc_u32 s27, s21, s27
	s_and_b64 s[28:29], s[0:1], exec
	s_cselect_b32 s25, s27, s31
	s_cselect_b32 s73, s26, s30
	s_ashr_i32 s23, s22, 31
	s_lshl_b64 s[28:29], s[22:23], 19
	s_add_u32 s28, s38, s28
	s_addc_u32 s29, s39, s29
	s_and_b64 s[34:35], s[0:1], exec
	s_cselect_b32 s23, s29, s5
	s_cselect_b32 s74, s28, s4
	s_add_u32 s75, s4, 0x100
	s_addc_u32 s81, s5, 0
	s_add_u32 s4, s30, 0x40080
	s_addc_u32 s5, s31, 0
	s_mov_b32 s82, -2
	v_mov_b64_e32 v[0:1], 0
	v_mov_b64_e32 v[2:3], 0
	v_mov_b64_e32 v[4:5], 0
	v_mov_b64_e32 v[6:7], 0
	v_mov_b64_e32 v[8:9], 0
	v_mov_b64_e32 v[10:11], 0
	v_mov_b64_e32 v[12:13], 0
	v_mov_b64_e32 v[14:15], 0
	v_mov_b64_e32 v[16:17], 0
	v_mov_b64_e32 v[18:19], 0
	v_mov_b64_e32 v[20:21], 0
	v_mov_b64_e32 v[22:23], 0
	v_mov_b64_e32 v[24:25], 0
	v_mov_b64_e32 v[26:27], 0
	v_mov_b64_e32 v[28:29], 0
	v_mov_b64_e32 v[30:31], 0
	v_mov_b64_e32 v[32:33], 0
	v_mov_b64_e32 v[34:35], 0
	v_mov_b64_e32 v[36:37], 0
	v_mov_b64_e32 v[38:39], 0
	v_mov_b64_e32 v[40:41], 0
	v_mov_b64_e32 v[42:43], 0
	v_mov_b64_e32 v[44:45], 0
	v_mov_b64_e32 v[46:47], 0
	v_mov_b64_e32 v[48:49], 0
	v_mov_b64_e32 v[50:51], 0
	v_mov_b64_e32 v[52:53], 0
	v_mov_b64_e32 v[54:55], 0
	v_mov_b64_e32 v[56:57], 0
	v_mov_b64_e32 v[58:59], 0
	v_mov_b64_e32 v[60:61], 0
	v_mov_b64_e32 v[62:63], 0
	v_mov_b64_e32 v[64:65], 0
	v_mov_b64_e32 v[66:67], 0
	v_mov_b64_e32 v[68:69], 0
	v_mov_b64_e32 v[70:71], 0
	v_mov_b64_e32 v[72:73], 0
	v_mov_b64_e32 v[74:75], 0
	v_mov_b64_e32 v[76:77], 0
	v_mov_b64_e32 v[78:79], 0
	v_mov_b64_e32 v[80:81], 0
	v_mov_b64_e32 v[82:83], 0
	v_mov_b64_e32 v[84:85], 0
	v_mov_b64_e32 v[86:87], 0
	v_mov_b64_e32 v[88:89], 0
	v_mov_b64_e32 v[90:91], 0
	v_mov_b64_e32 v[92:93], 0
	v_mov_b64_e32 v[94:95], 0
	v_mov_b64_e32 v[96:97], 0
	v_mov_b64_e32 v[98:99], 0
	v_mov_b64_e32 v[100:101], 0
	v_mov_b64_e32 v[102:103], 0
	v_mov_b64_e32 v[104:105], 0
	v_mov_b64_e32 v[106:107], 0
	v_mov_b64_e32 v[108:109], 0
	v_mov_b64_e32 v[110:111], 0
	v_mov_b64_e32 v[112:113], 0
	v_mov_b64_e32 v[114:115], 0
	v_mov_b64_e32 v[116:117], 0
	v_mov_b64_e32 v[118:119], 0
	v_mov_b64_e32 v[120:121], 0
	v_mov_b64_e32 v[122:123], 0
	v_mov_b64_e32 v[124:125], 0
	v_mov_b64_e32 v[126:127], 0

.LBB0_287:
	v_mov_b32_e32 v128, v157
	v_mov_b32_e32 v130, v163
	s_lshl_b32 s4, s2, 8
	s_add_i32 s4, s4, s60
	v_add_u32_e32 v180, s4, v128
	v_lshlrev_b32_e32 v128, 2, v130
	v_ashrrev_i32_e32 v129, 31, v128
	v_ashrrev_i32_e32 v181, 31, v180
	v_lshl_add_u64 v[160:161], v[128:129], 2, s[10:11]
	v_lshlrev_b64 v[128:129], 6, v[180:181]
	v_add_u32_e32 v174, 16, v180
	v_lshl_add_u64 v[128:129], v[160:161], 0, v[128:129]
	v_ashrrev_i32_e32 v175, 31, v174
	global_load_dwordx4 v[186:189], v[128:129], off
	v_lshlrev_b64 v[128:129], 6, v[174:175]
	v_lshl_add_u64 v[128:129], v[160:161], 0, v[128:129]
	global_load_dwordx4 v[190:193], v[128:129], off
	v_add_u32_e32 v170, 32, v180
	v_ashrrev_i32_e32 v171, 31, v170
	v_lshlrev_b64 v[128:129], 6, v[170:171]
	v_add_u32_e32 v166, 48, v180
	v_lshl_add_u64 v[128:129], v[160:161], 0, v[128:129]
	v_ashrrev_i32_e32 v167, 31, v166
	global_load_dwordx4 v[194:197], v[128:129], off
	v_lshlrev_b64 v[128:129], 6, v[166:167]
	v_lshl_add_u64 v[128:129], v[160:161], 0, v[128:129]
	global_load_dwordx4 v[198:201], v[128:129], off
	v_and_b32_e32 v129, 64, v185
	s_lshl_b32 s3, s3, 7
	v_xor_b32_e32 v128, 16, v185
	v_add_u32_e32 v129, 64, v129
	v_add_u32_e32 v164, 0x80, v180
	v_xor_b32_e32 v131, 32, v185
	s_or_b32 s3, s3, s61
	v_cmp_lt_i32_e32 vcc, v128, v129
	v_ashrrev_i32_e32 v165, 31, v164
	v_lshl_add_u32 v182, v130, 3, s3
	v_cndmask_b32_e32 v130, v185, v128, vcc
	v_cmp_lt_i32_e32 vcc, v131, v129
	v_add_u32_e32 v158, 0x90, v180
	v_lshlrev_b64 v[128:129], 6, v[164:165]
	v_lshl_add_u64 v[128:129], v[160:161], 0, v[128:129]
	v_ashrrev_i32_e32 v159, 31, v158
	global_load_dwordx4 v[202:205], v[128:129], off
	v_lshlrev_b64 v[128:129], 6, v[158:159]
	v_lshl_add_u64 v[128:129], v[160:161], 0, v[128:129]
	global_load_dwordx4 v[206:209], v[128:129], off
	s_ashr_i32 s2, s2, 5
	s_mul_hi_i32 s4, s2, 0x5800
	s_mulk_i32 s2, 0x5800
	s_add_u32 s2, s58, s2
	s_addc_u32 s3, s59, s4
	v_ashrrev_i32_e32 v183, 31, v182
	v_add_u32_e32 v154, 0xa0, v180
	v_add_u32_e32 v152, 0xb0, v180
	v_lshl_add_u64 v[210:211], v[182:183], 2, s[2:3]
	v_cndmask_b32_e32 v131, v185, v131, vcc
	v_ashrrev_i32_e32 v155, 31, v154
	v_ashrrev_i32_e32 v153, 31, v152
	v_add_co_u32_e32 v222, vcc, s56, v210
	v_lshlrev_b32_e32 v156, 2, v130
	v_lshlrev_b32_e32 v159, 2, v131
	v_lshl_add_u64 v[220:221], v[210:211], 0, s[16:17]
	global_load_dwordx4 v[128:131], v[210:211], off offset:16
	global_load_dwordx4 v[132:135], v[210:211], off
	v_addc_co_u32_e32 v223, vcc, 0, v211, vcc
	v_lshlrev_b64 v[210:211], 6, v[154:155]
	v_lshlrev_b64 v[212:213], 6, v[152:153]
	v_lshl_add_u64 v[210:211], v[160:161], 0, v[210:211]
	v_lshl_add_u64 v[160:161], v[160:161], 0, v[212:213]
	global_load_dwordx4 v[210:213], v[210:211], off
	s_nop 0
	global_load_dwordx4 v[214:217], v[160:161], off
	global_load_dwordx4 v[226:229], v[222:223], off offset:3072
	global_load_dwordx4 v[230:233], v[220:221], off offset:16
	v_mov_b64_e32 v[218:219], s[20:21]
	s_waitcnt vmcnt(0)
	v_mov_b32_e32 v160, v187
	v_mov_b32_e32 v161, v188
	v_mov_b32_e32 v187, v189
	v_pk_add_f32 v[160:161], v[160:161], v[186:187]
	v_mov_b32_e32 v186, v191
	v_mov_b32_e32 v187, v192
	v_mov_b32_e32 v191, v193
	v_pk_add_f32 v[186:187], v[186:187], v[190:191]
	v_mov_b32_e32 v189, v160
	v_mov_b32_e32 v188, v186
	v_mov_b32_e32 v160, v187
	v_pk_add_f32 v[160:161], v[188:189], v[160:161]
	ds_bpermute_b32 v187, v156, v161
	ds_bpermute_b32 v186, v156, v160
	v_mov_b32_e32 v188, v195
	v_mov_b32_e32 v189, v196
	v_mov_b32_e32 v195, v197
	v_mov_b32_e32 v190, v199
	s_waitcnt lgkmcnt(0)
	v_pk_add_f32 v[160:161], v[160:161], v[186:187]
	ds_bpermute_b32 v187, v159, v161
	ds_bpermute_b32 v186, v159, v160
	v_mov_b32_e32 v191, v200
	v_mov_b32_e32 v199, v201
	v_pk_add_f32 v[188:189], v[188:189], v[194:195]
	v_pk_add_f32 v[190:191], v[190:191], v[198:199]
	s_waitcnt lgkmcnt(0)
	v_pk_add_f32 v[160:161], v[160:161], v[186:187]
	v_mov_b32_e32 v186, v190
	v_mov_b32_e32 v187, v188
	v_mov_b32_e32 v188, v191
	v_pk_add_f32 v[186:187], v[186:187], v[188:189]
	ds_bpermute_b32 v189, v156, v187
	ds_bpermute_b32 v188, v156, v186
	v_pk_fma_f32 v[160:161], v[160:161], s[18:19], v[218:219] op_sel_hi:[1,0,0]
	v_mov_b32_e32 v198, v207
	v_mul_f32_e32 v153, 0x4b800000, v161
	v_cmp_gt_f32_e32 vcc, s67, v161
	v_mul_f32_e32 v155, 0x4b800000, v160
	v_cmp_gt_f32_e64 s[2:3], s67, v160
	v_cndmask_b32_e32 v153, v161, v153, vcc
	v_rsq_f32_e32 v153, v153
	v_cndmask_b32_e64 v155, v160, v155, s[2:3]
	s_waitcnt lgkmcnt(0)
	v_pk_add_f32 v[160:161], v[186:187], v[188:189]
	ds_bpermute_b32 v195, v159, v161
	ds_bpermute_b32 v194, v159, v160
	v_mov_b32_e32 v199, v208
	v_mov_b32_e32 v207, v209
	v_pk_add_f32 v[198:199], v[198:199], v[206:207]
	v_mul_f32_e32 v162, 0x45800000, v153
	s_waitcnt lgkmcnt(0)
	v_pk_add_f32 v[160:161], v[160:161], v[194:195]
	v_mov_b32_e32 v194, v203
	v_mov_b32_e32 v195, v204
	v_mov_b32_e32 v203, v205
	v_pk_add_f32 v[194:195], v[194:195], v[202:203]
	v_mov_b32_e32 v200, v198
	v_mov_b32_e32 v201, v194
	v_mov_b32_e32 v194, v199
	v_pk_add_f32 v[194:195], v[200:201], v[194:195]
	v_pk_fma_f32 v[160:161], v[160:161], s[18:19], v[218:219] op_sel_hi:[1,0,0]
	ds_bpermute_b32 v199, v156, v195
	ds_bpermute_b32 v198, v156, v194
	v_cndmask_b32_e32 v196, v153, v162, vcc
	v_mul_f32_e32 v162, 0x4b800000, v161
	v_cmp_gt_f32_e32 vcc, s67, v161
	v_cmp_gt_f32_e64 s[4:5], s67, v160
	v_rsq_f32_e32 v155, v155
	v_cndmask_b32_e32 v161, v161, v162, vcc
	v_rsq_f32_e32 v162, v161
	v_mul_f32_e32 v161, 0x4b800000, v160
	v_cndmask_b32_e64 v160, v160, v161, s[4:5]
	v_rsq_f32_e32 v165, v160
	s_waitcnt lgkmcnt(0)
	v_pk_add_f32 v[160:161], v[194:195], v[198:199]
	ds_bpermute_b32 v195, v159, v161
	ds_bpermute_b32 v194, v159, v160
	v_mov_b32_e32 v198, v215
	v_mov_b32_e32 v199, v216
	v_mov_b32_e32 v215, v217
	v_pk_add_f32 v[198:199], v[198:199], v[214:215]
	s_waitcnt lgkmcnt(0)
	v_pk_add_f32 v[160:161], v[160:161], v[194:195]
	v_mov_b32_e32 v194, v211
	v_mov_b32_e32 v195, v212
	v_mov_b32_e32 v211, v213
	v_pk_add_f32 v[194:195], v[194:195], v[210:211]
	v_mov_b32_e32 v200, v198
	v_mov_b32_e32 v201, v194
	v_mov_b32_e32 v194, v199
	v_pk_add_f32 v[194:195], v[200:201], v[194:195]
	ds_bpermute_b32 v199, v156, v195
	ds_bpermute_b32 v198, v156, v194
	v_mul_f32_e32 v153, 0x45800000, v155
	v_cndmask_b32_e64 v184, v155, v153, s[2:3]
	v_mul_f32_e32 v153, 0x45800000, v162
	v_pk_fma_f32 v[160:161], v[160:161], s[18:19], v[218:219] op_sel_hi:[1,0,0]
	v_cndmask_b32_e32 v178, v162, v153, vcc
	v_mul_f32_e32 v155, 0x4b800000, v161
	v_cmp_gt_f32_e32 vcc, s67, v161
	v_mul_f32_e32 v156, 0x4b800000, v160
	v_cmp_gt_f32_e64 s[2:3], s67, v160
	v_cndmask_b32_e32 v155, v161, v155, vcc
	v_rsq_f32_e32 v155, v155
	v_cndmask_b32_e64 v156, v160, v156, s[2:3]
	s_waitcnt lgkmcnt(0)
	v_pk_add_f32 v[160:161], v[194:195], v[198:199]
	ds_bpermute_b32 v195, v159, v161
	ds_bpermute_b32 v194, v159, v160
	v_mul_f32_e32 v153, 0x45800000, v165
	v_cndmask_b32_e64 v176, v165, v153, s[4:5]
	v_mul_f32_e32 v153, 0x45800000, v155
	v_cndmask_b32_e32 v172, v155, v153, vcc
	s_waitcnt lgkmcnt(0)
	v_pk_add_f32 v[160:161], v[160:161], v[194:195]
	v_rsq_f32_e32 v156, v156
	v_pk_fma_f32 v[160:161], v[160:161], s[18:19], v[218:219] op_sel_hi:[1,0,0]
	v_mul_f32_e32 v155, 0x4b800000, v161
	v_cmp_gt_f32_e32 vcc, s67, v161
	v_mul_f32_e32 v159, 0x4b800000, v160
	v_cmp_gt_f32_e64 s[4:5], s67, v160
	v_cndmask_b32_e32 v155, v161, v155, vcc
	v_rsq_f32_e32 v155, v155
	v_cndmask_b32_e64 v159, v160, v159, s[4:5]
	v_rsq_f32_e32 v159, v159
	v_mul_f32_e32 v153, 0x45800000, v156
	v_cndmask_b32_e64 v168, v156, v153, s[2:3]
	v_mul_f32_e32 v153, 0x45800000, v155
	v_cndmask_b32_e32 v162, v155, v153, vcc
	v_mul_f32_e32 v153, 0x45800000, v159
	v_cndmask_b32_e64 v156, v159, v153, s[4:5]
	s_waitcnt vmcnt(0)
	s_andn2_b64 vcc, exec, s[0:1]
	s_mov_b64 s[0:1], -1
	v_mov_b32_e32 v212, 0xbfb8aa3b
	v_mov_b64_e32 v[208:209], s[8:9]
	v_lshlrev_b64 v[210:211], 1, v[182:183]
	v_pk_fma_f32 v[124:125], v[124:125], v[196:197], v[132:133] op_sel_hi:[1,0,1]
	v_pk_fma_f32 v[126:127], v[126:127], v[196:197], v[134:135] op_sel_hi:[1,0,1]
	v_pk_fma_f32 v[116:117], v[116:117], v[196:197], v[128:129] op_sel_hi:[1,0,1]
	v_pk_fma_f32 v[118:119], v[118:119], v[196:197], v[130:131] op_sel_hi:[1,0,1]
	v_pk_mul_f32 v[198:199], v[124:125], v[212:213] op_sel_hi:[1,0]
	v_pk_mul_f32 v[200:201], v[126:127], v[212:213] op_sel_hi:[1,0]
	v_pk_mul_f32 v[202:203], v[116:117], v[212:213] op_sel_hi:[1,0]
	v_pk_mul_f32 v[204:205], v[118:119], v[212:213] op_sel_hi:[1,0]
	v_exp_f32_e32 v198, v198
	v_exp_f32_e32 v199, v199
	v_exp_f32_e32 v200, v200
	v_exp_f32_e32 v201, v201
	v_exp_f32_e32 v202, v202
	v_exp_f32_e32 v203, v203
	v_exp_f32_e32 v204, v204
	v_exp_f32_e32 v205, v205
	v_pk_fma_f32 v[120:121], v[120:121], v[196:197], v[226:227] op_sel_hi:[1,0,1]
	v_pk_fma_f32 v[122:123], v[122:123], v[196:197], v[228:229] op_sel_hi:[1,0,1]
	v_pk_fma_f32 v[112:113], v[112:113], v[196:197], v[230:231] op_sel_hi:[1,0,1]
	v_pk_fma_f32 v[114:115], v[114:115], v[196:197], v[232:233] op_sel_hi:[1,0,1]
	v_pk_add_f32 v[198:199], v[198:199], 1.0 op_sel_hi:[1,0]
	v_pk_add_f32 v[200:201], v[200:201], 1.0 op_sel_hi:[1,0]
	v_pk_add_f32 v[202:203], v[202:203], 1.0 op_sel_hi:[1,0]
	v_pk_add_f32 v[204:205], v[204:205], 1.0 op_sel_hi:[1,0]
	v_rcp_f32_e32 v198, v198
	v_rcp_f32_e32 v199, v199
	v_rcp_f32_e32 v200, v200
	v_rcp_f32_e32 v201, v201
	v_rcp_f32_e32 v202, v202
	v_rcp_f32_e32 v203, v203
	v_rcp_f32_e32 v204, v204
	v_rcp_f32_e32 v205, v205
	v_mad_i64_i32 v[206:207], s[2:3], v180, s72, v[208:209]
	v_pk_mul_f32 v[124:125], v[124:125], v[198:199]
	v_pk_mul_f32 v[126:127], v[126:127], v[200:201]
	v_pk_mul_f32 v[116:117], v[116:117], v[202:203]
	v_pk_mul_f32 v[118:119], v[118:119], v[204:205]
	v_lshl_add_u64 v[206:207], v[206:207], 0, v[210:211]
	v_pk_mul_f32 v[124:125], v[124:125], v[120:121]
	v_pk_mul_f32 v[126:127], v[126:127], v[122:123]
	v_pk_mul_f32 v[116:117], v[116:117], v[112:113]
	v_pk_mul_f32 v[118:119], v[118:119], v[114:115]
	v_cvt_pk_bf16_f32 v198, v124, v125
	v_cvt_pk_bf16_f32 v199, v126, v127
	v_cvt_pk_bf16_f32 v200, v116, v117
	v_cvt_pk_bf16_f32 v201, v118, v119
	global_store_dwordx4 v[206:207], v[198:201], off
	v_pk_fma_f32 v[108:109], v[108:109], v[184:185], v[132:133] op_sel_hi:[1,0,1]
	v_pk_fma_f32 v[110:111], v[110:111], v[184:185], v[134:135] op_sel_hi:[1,0,1]
	v_pk_fma_f32 v[100:101], v[100:101], v[184:185], v[128:129] op_sel_hi:[1,0,1]
	v_pk_fma_f32 v[102:103], v[102:103], v[184:185], v[130:131] op_sel_hi:[1,0,1]
	v_pk_mul_f32 v[198:199], v[108:109], v[212:213] op_sel_hi:[1,0]
	v_pk_mul_f32 v[200:201], v[110:111], v[212:213] op_sel_hi:[1,0]
	v_pk_mul_f32 v[202:203], v[100:101], v[212:213] op_sel_hi:[1,0]
	v_pk_mul_f32 v[204:205], v[102:103], v[212:213] op_sel_hi:[1,0]
	v_exp_f32_e32 v198, v198
	v_exp_f32_e32 v199, v199
	v_exp_f32_e32 v200, v200
	v_exp_f32_e32 v201, v201
	v_exp_f32_e32 v202, v202
	v_exp_f32_e32 v203, v203
	v_exp_f32_e32 v204, v204
	v_exp_f32_e32 v205, v205
	v_pk_fma_f32 v[104:105], v[104:105], v[184:185], v[226:227] op_sel_hi:[1,0,1]
	v_pk_fma_f32 v[106:107], v[106:107], v[184:185], v[228:229] op_sel_hi:[1,0,1]
	v_pk_fma_f32 v[96:97], v[96:97], v[184:185], v[230:231] op_sel_hi:[1,0,1]
	v_pk_fma_f32 v[98:99], v[98:99], v[184:185], v[232:233] op_sel_hi:[1,0,1]
	v_pk_add_f32 v[198:199], v[198:199], 1.0 op_sel_hi:[1,0]
	v_pk_add_f32 v[200:201], v[200:201], 1.0 op_sel_hi:[1,0]
	v_pk_add_f32 v[202:203], v[202:203], 1.0 op_sel_hi:[1,0]
	v_pk_add_f32 v[204:205], v[204:205], 1.0 op_sel_hi:[1,0]
	v_rcp_f32_e32 v198, v198
	v_rcp_f32_e32 v199, v199
	v_rcp_f32_e32 v200, v200
	v_rcp_f32_e32 v201, v201
	v_rcp_f32_e32 v202, v202
	v_rcp_f32_e32 v203, v203
	v_rcp_f32_e32 v204, v204
	v_rcp_f32_e32 v205, v205
	v_mad_i64_i32 v[206:207], s[2:3], v174, s72, v[208:209]
	v_pk_mul_f32 v[108:109], v[108:109], v[198:199]
	v_pk_mul_f32 v[110:111], v[110:111], v[200:201]
	v_pk_mul_f32 v[100:101], v[100:101], v[202:203]
	v_pk_mul_f32 v[102:103], v[102:103], v[204:205]
	v_lshl_add_u64 v[206:207], v[206:207], 0, v[210:211]
	v_pk_mul_f32 v[108:109], v[108:109], v[104:105]
	v_pk_mul_f32 v[110:111], v[110:111], v[106:107]
	v_pk_mul_f32 v[100:101], v[100:101], v[96:97]
	v_pk_mul_f32 v[102:103], v[102:103], v[98:99]
	v_cvt_pk_bf16_f32 v198, v108, v109
	v_cvt_pk_bf16_f32 v199, v110, v111
	v_cvt_pk_bf16_f32 v200, v100, v101
	v_cvt_pk_bf16_f32 v201, v102, v103
	global_store_dwordx4 v[206:207], v[198:201], off
	v_pk_fma_f32 v[92:93], v[92:93], v[178:179], v[132:133] op_sel_hi:[1,0,1]
	v_pk_fma_f32 v[94:95], v[94:95], v[178:179], v[134:135] op_sel_hi:[1,0,1]
	v_pk_fma_f32 v[84:85], v[84:85], v[178:179], v[128:129] op_sel_hi:[1,0,1]
	v_pk_fma_f32 v[86:87], v[86:87], v[178:179], v[130:131] op_sel_hi:[1,0,1]
	v_pk_mul_f32 v[198:199], v[92:93], v[212:213] op_sel_hi:[1,0]
	v_pk_mul_f32 v[200:201], v[94:95], v[212:213] op_sel_hi:[1,0]
	v_pk_mul_f32 v[202:203], v[84:85], v[212:213] op_sel_hi:[1,0]
	v_pk_mul_f32 v[204:205], v[86:87], v[212:213] op_sel_hi:[1,0]
	v_exp_f32_e32 v198, v198
	v_exp_f32_e32 v199, v199
	v_exp_f32_e32 v200, v200
	v_exp_f32_e32 v201, v201
	v_exp_f32_e32 v202, v202
	v_exp_f32_e32 v203, v203
	v_exp_f32_e32 v204, v204
	v_exp_f32_e32 v205, v205
	v_pk_fma_f32 v[88:89], v[88:89], v[178:179], v[226:227] op_sel_hi:[1,0,1]
	v_pk_fma_f32 v[90:91], v[90:91], v[178:179], v[228:229] op_sel_hi:[1,0,1]
	v_pk_fma_f32 v[80:81], v[80:81], v[178:179], v[230:231] op_sel_hi:[1,0,1]
	v_pk_fma_f32 v[82:83], v[82:83], v[178:179], v[232:233] op_sel_hi:[1,0,1]
	v_pk_add_f32 v[198:199], v[198:199], 1.0 op_sel_hi:[1,0]
	v_pk_add_f32 v[200:201], v[200:201], 1.0 op_sel_hi:[1,0]
	v_pk_add_f32 v[202:203], v[202:203], 1.0 op_sel_hi:[1,0]
	v_pk_add_f32 v[204:205], v[204:205], 1.0 op_sel_hi:[1,0]
	v_rcp_f32_e32 v198, v198
	v_rcp_f32_e32 v199, v199
	v_rcp_f32_e32 v200, v200
	v_rcp_f32_e32 v201, v201
	v_rcp_f32_e32 v202, v202
	v_rcp_f32_e32 v203, v203
	v_rcp_f32_e32 v204, v204
	v_rcp_f32_e32 v205, v205
	v_mad_i64_i32 v[206:207], s[2:3], v170, s72, v[208:209]
	v_pk_mul_f32 v[92:93], v[92:93], v[198:199]
	v_pk_mul_f32 v[94:95], v[94:95], v[200:201]
	v_pk_mul_f32 v[84:85], v[84:85], v[202:203]
	v_pk_mul_f32 v[86:87], v[86:87], v[204:205]
	v_lshl_add_u64 v[206:207], v[206:207], 0, v[210:211]
	v_pk_mul_f32 v[92:93], v[92:93], v[88:89]
	v_pk_mul_f32 v[94:95], v[94:95], v[90:91]
	v_pk_mul_f32 v[84:85], v[84:85], v[80:81]
	v_pk_mul_f32 v[86:87], v[86:87], v[82:83]
	v_cvt_pk_bf16_f32 v198, v92, v93
	v_cvt_pk_bf16_f32 v199, v94, v95
	v_cvt_pk_bf16_f32 v200, v84, v85
	v_cvt_pk_bf16_f32 v201, v86, v87
	global_store_dwordx4 v[206:207], v[198:201], off
	v_pk_fma_f32 v[76:77], v[76:77], v[176:177], v[132:133] op_sel_hi:[1,0,1]
	v_pk_fma_f32 v[78:79], v[78:79], v[176:177], v[134:135] op_sel_hi:[1,0,1]
	v_pk_fma_f32 v[68:69], v[68:69], v[176:177], v[128:129] op_sel_hi:[1,0,1]
	v_pk_fma_f32 v[70:71], v[70:71], v[176:177], v[130:131] op_sel_hi:[1,0,1]
	v_pk_mul_f32 v[198:199], v[76:77], v[212:213] op_sel_hi:[1,0]
	v_pk_mul_f32 v[200:201], v[78:79], v[212:213] op_sel_hi:[1,0]
	v_pk_mul_f32 v[202:203], v[68:69], v[212:213] op_sel_hi:[1,0]
	v_pk_mul_f32 v[204:205], v[70:71], v[212:213] op_sel_hi:[1,0]
	v_exp_f32_e32 v198, v198
	v_exp_f32_e32 v199, v199
	v_exp_f32_e32 v200, v200
	v_exp_f32_e32 v201, v201
	v_exp_f32_e32 v202, v202
	v_exp_f32_e32 v203, v203
	v_exp_f32_e32 v204, v204
	v_exp_f32_e32 v205, v205
	v_pk_fma_f32 v[72:73], v[72:73], v[176:177], v[226:227] op_sel_hi:[1,0,1]
	v_pk_fma_f32 v[74:75], v[74:75], v[176:177], v[228:229] op_sel_hi:[1,0,1]
	v_pk_fma_f32 v[64:65], v[64:65], v[176:177], v[230:231] op_sel_hi:[1,0,1]
	v_pk_fma_f32 v[66:67], v[66:67], v[176:177], v[232:233] op_sel_hi:[1,0,1]
	v_pk_add_f32 v[198:199], v[198:199], 1.0 op_sel_hi:[1,0]
	v_pk_add_f32 v[200:201], v[200:201], 1.0 op_sel_hi:[1,0]
	v_pk_add_f32 v[202:203], v[202:203], 1.0 op_sel_hi:[1,0]
	v_pk_add_f32 v[204:205], v[204:205], 1.0 op_sel_hi:[1,0]
	v_rcp_f32_e32 v198, v198
	v_rcp_f32_e32 v199, v199
	v_rcp_f32_e32 v200, v200
	v_rcp_f32_e32 v201, v201
	v_rcp_f32_e32 v202, v202
	v_rcp_f32_e32 v203, v203
	v_rcp_f32_e32 v204, v204
	v_rcp_f32_e32 v205, v205
	v_mad_i64_i32 v[206:207], s[2:3], v166, s72, v[208:209]
	v_pk_mul_f32 v[76:77], v[76:77], v[198:199]
	v_pk_mul_f32 v[78:79], v[78:79], v[200:201]
	v_pk_mul_f32 v[68:69], v[68:69], v[202:203]
	v_pk_mul_f32 v[70:71], v[70:71], v[204:205]
	v_lshl_add_u64 v[206:207], v[206:207], 0, v[210:211]
	v_pk_mul_f32 v[76:77], v[76:77], v[72:73]
	v_pk_mul_f32 v[78:79], v[78:79], v[74:75]
	v_pk_mul_f32 v[68:69], v[68:69], v[64:65]
	v_pk_mul_f32 v[70:71], v[70:71], v[66:67]
	v_cvt_pk_bf16_f32 v198, v76, v77
	v_cvt_pk_bf16_f32 v199, v78, v79
	v_cvt_pk_bf16_f32 v200, v68, v69
	v_cvt_pk_bf16_f32 v201, v70, v71
	global_store_dwordx4 v[206:207], v[198:201], off
	v_pk_fma_f32 v[60:61], v[60:61], v[172:173], v[132:133] op_sel_hi:[1,0,1]
	v_pk_fma_f32 v[62:63], v[62:63], v[172:173], v[134:135] op_sel_hi:[1,0,1]
	v_pk_fma_f32 v[52:53], v[52:53], v[172:173], v[128:129] op_sel_hi:[1,0,1]
	v_pk_fma_f32 v[54:55], v[54:55], v[172:173], v[130:131] op_sel_hi:[1,0,1]
	v_pk_mul_f32 v[198:199], v[60:61], v[212:213] op_sel_hi:[1,0]
	v_pk_mul_f32 v[200:201], v[62:63], v[212:213] op_sel_hi:[1,0]
	v_pk_mul_f32 v[202:203], v[52:53], v[212:213] op_sel_hi:[1,0]
	v_pk_mul_f32 v[204:205], v[54:55], v[212:213] op_sel_hi:[1,0]
	v_exp_f32_e32 v198, v198
	v_exp_f32_e32 v199, v199
	v_exp_f32_e32 v200, v200
	v_exp_f32_e32 v201, v201
	v_exp_f32_e32 v202, v202
	v_exp_f32_e32 v203, v203
	v_exp_f32_e32 v204, v204
	v_exp_f32_e32 v205, v205
	v_pk_fma_f32 v[56:57], v[56:57], v[172:173], v[226:227] op_sel_hi:[1,0,1]
	v_pk_fma_f32 v[58:59], v[58:59], v[172:173], v[228:229] op_sel_hi:[1,0,1]
	v_pk_fma_f32 v[48:49], v[48:49], v[172:173], v[230:231] op_sel_hi:[1,0,1]
	v_pk_fma_f32 v[50:51], v[50:51], v[172:173], v[232:233] op_sel_hi:[1,0,1]
	v_pk_add_f32 v[198:199], v[198:199], 1.0 op_sel_hi:[1,0]
	v_pk_add_f32 v[200:201], v[200:201], 1.0 op_sel_hi:[1,0]
	v_pk_add_f32 v[202:203], v[202:203], 1.0 op_sel_hi:[1,0]
	v_pk_add_f32 v[204:205], v[204:205], 1.0 op_sel_hi:[1,0]
	v_rcp_f32_e32 v198, v198
	v_rcp_f32_e32 v199, v199
	v_rcp_f32_e32 v200, v200
	v_rcp_f32_e32 v201, v201
	v_rcp_f32_e32 v202, v202
	v_rcp_f32_e32 v203, v203
	v_rcp_f32_e32 v204, v204
	v_rcp_f32_e32 v205, v205
	v_mad_i64_i32 v[206:207], s[2:3], v164, s72, v[208:209]
	v_pk_mul_f32 v[60:61], v[60:61], v[198:199]
	v_pk_mul_f32 v[62:63], v[62:63], v[200:201]
	v_pk_mul_f32 v[52:53], v[52:53], v[202:203]
	v_pk_mul_f32 v[54:55], v[54:55], v[204:205]
	v_lshl_add_u64 v[206:207], v[206:207], 0, v[210:211]
	v_pk_mul_f32 v[60:61], v[60:61], v[56:57]
	v_pk_mul_f32 v[62:63], v[62:63], v[58:59]
	v_pk_mul_f32 v[52:53], v[52:53], v[48:49]
	v_pk_mul_f32 v[54:55], v[54:55], v[50:51]
	v_cvt_pk_bf16_f32 v198, v60, v61
	v_cvt_pk_bf16_f32 v199, v62, v63
	v_cvt_pk_bf16_f32 v200, v52, v53
	v_cvt_pk_bf16_f32 v201, v54, v55
	global_store_dwordx4 v[206:207], v[198:201], off
	v_pk_fma_f32 v[44:45], v[44:45], v[168:169], v[132:133] op_sel_hi:[1,0,1]
	v_pk_fma_f32 v[46:47], v[46:47], v[168:169], v[134:135] op_sel_hi:[1,0,1]
	v_pk_fma_f32 v[36:37], v[36:37], v[168:169], v[128:129] op_sel_hi:[1,0,1]
	v_pk_fma_f32 v[38:39], v[38:39], v[168:169], v[130:131] op_sel_hi:[1,0,1]
	v_pk_mul_f32 v[198:199], v[44:45], v[212:213] op_sel_hi:[1,0]
	v_pk_mul_f32 v[200:201], v[46:47], v[212:213] op_sel_hi:[1,0]
	v_pk_mul_f32 v[202:203], v[36:37], v[212:213] op_sel_hi:[1,0]
	v_pk_mul_f32 v[204:205], v[38:39], v[212:213] op_sel_hi:[1,0]
	v_exp_f32_e32 v198, v198
	v_exp_f32_e32 v199, v199
	v_exp_f32_e32 v200, v200
	v_exp_f32_e32 v201, v201
	v_exp_f32_e32 v202, v202
	v_exp_f32_e32 v203, v203
	v_exp_f32_e32 v204, v204
	v_exp_f32_e32 v205, v205
	v_pk_fma_f32 v[40:41], v[40:41], v[168:169], v[226:227] op_sel_hi:[1,0,1]
	v_pk_fma_f32 v[42:43], v[42:43], v[168:169], v[228:229] op_sel_hi:[1,0,1]
	v_pk_fma_f32 v[32:33], v[32:33], v[168:169], v[230:231] op_sel_hi:[1,0,1]
	v_pk_fma_f32 v[34:35], v[34:35], v[168:169], v[232:233] op_sel_hi:[1,0,1]
	v_pk_add_f32 v[198:199], v[198:199], 1.0 op_sel_hi:[1,0]
	v_pk_add_f32 v[200:201], v[200:201], 1.0 op_sel_hi:[1,0]
	v_pk_add_f32 v[202:203], v[202:203], 1.0 op_sel_hi:[1,0]
	v_pk_add_f32 v[204:205], v[204:205], 1.0 op_sel_hi:[1,0]
	v_rcp_f32_e32 v198, v198
	v_rcp_f32_e32 v199, v199
	v_rcp_f32_e32 v200, v200
	v_rcp_f32_e32 v201, v201
	v_rcp_f32_e32 v202, v202
	v_rcp_f32_e32 v203, v203
	v_rcp_f32_e32 v204, v204
	v_rcp_f32_e32 v205, v205
	v_mad_i64_i32 v[206:207], s[2:3], v158, s72, v[208:209]
	v_pk_mul_f32 v[44:45], v[44:45], v[198:199]
	v_pk_mul_f32 v[46:47], v[46:47], v[200:201]
	v_pk_mul_f32 v[36:37], v[36:37], v[202:203]
	v_pk_mul_f32 v[38:39], v[38:39], v[204:205]
	v_lshl_add_u64 v[206:207], v[206:207], 0, v[210:211]
	v_pk_mul_f32 v[44:45], v[44:45], v[40:41]
	v_pk_mul_f32 v[46:47], v[46:47], v[42:43]
	v_pk_mul_f32 v[36:37], v[36:37], v[32:33]
	v_pk_mul_f32 v[38:39], v[38:39], v[34:35]
	v_cvt_pk_bf16_f32 v198, v44, v45
	v_cvt_pk_bf16_f32 v199, v46, v47
	v_cvt_pk_bf16_f32 v200, v36, v37
	v_cvt_pk_bf16_f32 v201, v38, v39
	global_store_dwordx4 v[206:207], v[198:201], off
	v_pk_fma_f32 v[28:29], v[28:29], v[162:163], v[132:133] op_sel_hi:[1,0,1]
	v_pk_fma_f32 v[30:31], v[30:31], v[162:163], v[134:135] op_sel_hi:[1,0,1]
	v_pk_fma_f32 v[20:21], v[20:21], v[162:163], v[128:129] op_sel_hi:[1,0,1]
	v_pk_fma_f32 v[22:23], v[22:23], v[162:163], v[130:131] op_sel_hi:[1,0,1]
	v_pk_mul_f32 v[198:199], v[28:29], v[212:213] op_sel_hi:[1,0]
	v_pk_mul_f32 v[200:201], v[30:31], v[212:213] op_sel_hi:[1,0]
	v_pk_mul_f32 v[202:203], v[20:21], v[212:213] op_sel_hi:[1,0]
	v_pk_mul_f32 v[204:205], v[22:23], v[212:213] op_sel_hi:[1,0]
	v_exp_f32_e32 v198, v198
	v_exp_f32_e32 v199, v199
	v_exp_f32_e32 v200, v200
	v_exp_f32_e32 v201, v201
	v_exp_f32_e32 v202, v202
	v_exp_f32_e32 v203, v203
	v_exp_f32_e32 v204, v204
	v_exp_f32_e32 v205, v205
	v_pk_fma_f32 v[24:25], v[24:25], v[162:163], v[226:227] op_sel_hi:[1,0,1]
	v_pk_fma_f32 v[26:27], v[26:27], v[162:163], v[228:229] op_sel_hi:[1,0,1]
	v_pk_fma_f32 v[16:17], v[16:17], v[162:163], v[230:231] op_sel_hi:[1,0,1]
	v_pk_fma_f32 v[18:19], v[18:19], v[162:163], v[232:233] op_sel_hi:[1,0,1]
	v_pk_add_f32 v[198:199], v[198:199], 1.0 op_sel_hi:[1,0]
	v_pk_add_f32 v[200:201], v[200:201], 1.0 op_sel_hi:[1,0]
	v_pk_add_f32 v[202:203], v[202:203], 1.0 op_sel_hi:[1,0]
	v_pk_add_f32 v[204:205], v[204:205], 1.0 op_sel_hi:[1,0]
	v_rcp_f32_e32 v198, v198
	v_rcp_f32_e32 v199, v199
	v_rcp_f32_e32 v200, v200
	v_rcp_f32_e32 v201, v201
	v_rcp_f32_e32 v202, v202
	v_rcp_f32_e32 v203, v203
	v_rcp_f32_e32 v204, v204
	v_rcp_f32_e32 v205, v205
	v_mad_i64_i32 v[206:207], s[2:3], v154, s72, v[208:209]
	v_pk_mul_f32 v[28:29], v[28:29], v[198:199]
	v_pk_mul_f32 v[30:31], v[30:31], v[200:201]
	v_pk_mul_f32 v[20:21], v[20:21], v[202:203]
	v_pk_mul_f32 v[22:23], v[22:23], v[204:205]
	v_lshl_add_u64 v[206:207], v[206:207], 0, v[210:211]
	v_pk_mul_f32 v[28:29], v[28:29], v[24:25]
	v_pk_mul_f32 v[30:31], v[30:31], v[26:27]
	v_pk_mul_f32 v[20:21], v[20:21], v[16:17]
	v_pk_mul_f32 v[22:23], v[22:23], v[18:19]
	v_cvt_pk_bf16_f32 v198, v28, v29
	v_cvt_pk_bf16_f32 v199, v30, v31
	v_cvt_pk_bf16_f32 v200, v20, v21
	v_cvt_pk_bf16_f32 v201, v22, v23
	global_store_dwordx4 v[206:207], v[198:201], off
	v_pk_fma_f32 v[12:13], v[12:13], v[156:157], v[132:133] op_sel_hi:[1,0,1]
	v_pk_fma_f32 v[14:15], v[14:15], v[156:157], v[134:135] op_sel_hi:[1,0,1]
	v_pk_fma_f32 v[4:5], v[4:5], v[156:157], v[128:129] op_sel_hi:[1,0,1]
	v_pk_fma_f32 v[6:7], v[6:7], v[156:157], v[130:131] op_sel_hi:[1,0,1]
	v_pk_mul_f32 v[198:199], v[12:13], v[212:213] op_sel_hi:[1,0]
	v_pk_mul_f32 v[200:201], v[14:15], v[212:213] op_sel_hi:[1,0]
	v_pk_mul_f32 v[202:203], v[4:5], v[212:213] op_sel_hi:[1,0]
	v_pk_mul_f32 v[204:205], v[6:7], v[212:213] op_sel_hi:[1,0]
	v_exp_f32_e32 v198, v198
	v_exp_f32_e32 v199, v199
	v_exp_f32_e32 v200, v200
	v_exp_f32_e32 v201, v201
	v_exp_f32_e32 v202, v202
	v_exp_f32_e32 v203, v203
	v_exp_f32_e32 v204, v204
	v_exp_f32_e32 v205, v205
	v_pk_fma_f32 v[8:9], v[8:9], v[156:157], v[226:227] op_sel_hi:[1,0,1]
	v_pk_fma_f32 v[10:11], v[10:11], v[156:157], v[228:229] op_sel_hi:[1,0,1]
	v_pk_fma_f32 v[0:1], v[0:1], v[156:157], v[230:231] op_sel_hi:[1,0,1]
	v_pk_fma_f32 v[2:3], v[2:3], v[156:157], v[232:233] op_sel_hi:[1,0,1]
	v_pk_add_f32 v[198:199], v[198:199], 1.0 op_sel_hi:[1,0]
	v_pk_add_f32 v[200:201], v[200:201], 1.0 op_sel_hi:[1,0]
	v_pk_add_f32 v[202:203], v[202:203], 1.0 op_sel_hi:[1,0]
	v_pk_add_f32 v[204:205], v[204:205], 1.0 op_sel_hi:[1,0]
	v_rcp_f32_e32 v198, v198
	v_rcp_f32_e32 v199, v199
	v_rcp_f32_e32 v200, v200
	v_rcp_f32_e32 v201, v201
	v_rcp_f32_e32 v202, v202
	v_rcp_f32_e32 v203, v203
	v_rcp_f32_e32 v204, v204
	v_rcp_f32_e32 v205, v205
	v_mad_i64_i32 v[206:207], s[2:3], v152, s72, v[208:209]
	v_pk_mul_f32 v[12:13], v[12:13], v[198:199]
	v_pk_mul_f32 v[14:15], v[14:15], v[200:201]
	v_pk_mul_f32 v[4:5], v[4:5], v[202:203]
	v_pk_mul_f32 v[6:7], v[6:7], v[204:205]
	v_lshl_add_u64 v[206:207], v[206:207], 0, v[210:211]
	v_pk_mul_f32 v[12:13], v[12:13], v[8:9]
	v_pk_mul_f32 v[14:15], v[14:15], v[10:11]
	v_pk_mul_f32 v[4:5], v[4:5], v[0:1]
	v_pk_mul_f32 v[6:7], v[6:7], v[2:3]
	v_cvt_pk_bf16_f32 v198, v12, v13
	v_cvt_pk_bf16_f32 v199, v14, v15
	v_cvt_pk_bf16_f32 v200, v4, v5
	v_cvt_pk_bf16_f32 v201, v6, v7
	global_store_dwordx4 v[206:207], v[198:201], off
	s_cbranch_vccnz .LBB0_280
	s_andn2_b64 vcc, exec, s[6:7]
	s_cbranch_vccnz .LBB0_279
	s_barrier
	s_branch .LBB0_279

.LBB0_361:
	s_lshl_b32 s18, s66, 8
	s_add_i32 s18, s18, s44
	v_add_u32_e32 v217, s18, v230
	s_lshl_b32 s19, s65, 8
	s_or_b32 s19, s19, s45
	v_lshl_add_u32 v218, v231, 3, s19
	v_lshlrev_b32_e32 v219, 2, v218
	s_ashr_i32 s18, s66, 5
	s_mul_hi_i32 s21, s18, 0x9000
	s_mul_i32 s20, s18, 0x9000
	s_add_u32 s20, s40, s20
	s_addc_u32 s21, s41, s21
	s_ashr_i32 s19, s18, 31
	s_lshl_b64 s[18:19], s[18:19], 12
	s_add_u32 s18, s42, s18
	s_addc_u32 s19, s43, s19
	v_lshl_add_u32 v237, v217, 12, v219
	global_load_dwordx4 v[96:99], v219, s[20:21] offset:0
	global_load_dwordx4 v[100:103], v219, s[20:21] offset:16
	global_load_dwordx4 v[152:155], v219, s[18:19] offset:0
	global_load_dwordx4 v[156:159], v219, s[18:19] offset:16
	s_add_u32 s20, s52, 0x0
	s_addc_u32 s21, s53, 0
	global_load_dwordx4 v[160:163], v237, s[20:21] offset:0
	global_load_dwordx4 v[164:167], v237, s[20:21] offset:16
	s_add_u32 s20, s52, 0x10000
	s_addc_u32 s21, s53, 0
	global_load_dwordx4 v[168:171], v237, s[20:21] offset:0
	global_load_dwordx4 v[172:175], v237, s[20:21] offset:16
	s_add_u32 s20, s52, 0x20000
	s_addc_u32 s21, s53, 0
	global_load_dwordx4 v[176:179], v237, s[20:21] offset:0
	global_load_dwordx4 v[180:183], v237, s[20:21] offset:16
	s_add_u32 s20, s52, 0x30000
	s_addc_u32 s21, s53, 0
	global_load_dwordx4 v[184:187], v237, s[20:21] offset:0
	global_load_dwordx4 v[188:191], v237, s[20:21] offset:16
	s_add_u32 s20, s52, 0x80000
	s_addc_u32 s21, s53, 0
	global_load_dwordx4 v[192:195], v237, s[20:21] offset:0
	global_load_dwordx4 v[196:199], v237, s[20:21] offset:16
	s_add_u32 s20, s52, 0x90000
	s_addc_u32 s21, s53, 0
	global_load_dwordx4 v[200:203], v237, s[20:21] offset:0
	global_load_dwordx4 v[204:207], v237, s[20:21] offset:16
	s_add_u32 s20, s52, 0xa0000
	s_addc_u32 s21, s53, 0
	global_load_dwordx4 v[208:211], v237, s[20:21] offset:0
	global_load_dwordx4 v[212:215], v237, s[20:21] offset:16
	v_lshlrev_b32_e32 v238, 1, v218
	v_lshl_add_u32 v238, v217, 11, v238
	v_lshlrev_b32_e32 v248, 6, v217
	v_xor_b32_e32 v249, 16, v236
	v_lshlrev_b32_e32 v249, 2, v249
	v_xor_b32_e32 v216, 32, v236
	v_lshlrev_b32_e32 v216, 2, v216
	s_waitcnt vmcnt(12)
	v_pk_mul_f32 v[96:97], v[96:97], 0.5 op_sel_hi:[1,0]
	v_pk_mul_f32 v[98:99], v[98:99], 0.5 op_sel_hi:[1,0]
	v_pk_mul_f32 v[100:101], v[100:101], 0.5 op_sel_hi:[1,0]
	v_pk_mul_f32 v[102:103], v[102:103], 0.5 op_sel_hi:[1,0]
	v_pk_fma_f32 v[160:161], v[132:133], v[96:97], v[160:161]
	v_pk_fma_f32 v[162:163], v[134:135], v[98:99], v[162:163]
	v_pk_fma_f32 v[164:165], v[128:129], v[100:101], v[164:165]
	v_pk_fma_f32 v[166:167], v[130:131], v[102:103], v[166:167]
	v_pk_mul_f32 v[220:221], v[160:161], v[152:153]
	v_pk_mul_f32 v[222:223], v[162:163], v[154:155]
	v_pk_mul_f32 v[224:225], v[164:165], v[156:157]
	v_pk_mul_f32 v[226:227], v[166:167], v[158:159]
	v_cvt_pk_bf16_f32 v132, v160, v161
	v_cvt_pk_bf16_f32 v133, v162, v163
	v_cvt_pk_bf16_f32 v134, v164, v165
	v_cvt_pk_bf16_f32 v135, v166, v167
	v_cvt_pk_bf16_f32 v128, v220, v221
	v_cvt_pk_bf16_f32 v129, v222, v223
	v_cvt_pk_bf16_f32 v130, v224, v225
	v_cvt_pk_bf16_f32 v131, v226, v227
	s_add_u32 s18, s6, 0x0
	s_addc_u32 s19, s7, 0
	global_store_dwordx4 v238, v[132:135], s[18:19] offset:0
	s_add_u32 s20, s10, 0x0
	s_addc_u32 s21, s11, 0
	global_store_dwordx4 v238, v[128:131], s[20:21] offset:0
	v_pk_mul_f32 v[220:221], v[160:161], v[160:161]
	v_pk_mul_f32 v[222:223], v[162:163], v[162:163]
	v_pk_mul_f32 v[224:225], v[164:165], v[164:165]
	v_pk_mul_f32 v[226:227], v[166:167], v[166:167]
	v_add_f32_e32 v220, v220, v221
	v_add_f32_e32 v222, v222, v223
	v_add_f32_e32 v224, v224, v225
	v_add_f32_e32 v226, v226, v227
	v_add_f32_e32 v220, v220, v222
	v_add_f32_e32 v224, v224, v226
	v_add_f32_e32 v240, v220, v224
	s_ashr_i32 s18, s66, 5
	s_mul_hi_i32 s21, s18, 0x9000
	s_mul_i32 s20, s18, 0x9000
	s_add_u32 s20, s40, s20
	s_addc_u32 s21, s41, s21
	s_ashr_i32 s19, s18, 31
	s_lshl_b64 s[18:19], s[18:19], 12
	s_add_u32 s18, s42, s18
	s_addc_u32 s19, s43, s19
	global_load_dwordx4 v[160:163], v219, s[20:21] offset:512
	global_load_dwordx4 v[164:167], v219, s[20:21] offset:528
	global_load_dwordx4 v[132:135], v219, s[18:19] offset:512
	global_load_dwordx4 v[128:131], v219, s[18:19] offset:528
	s_waitcnt vmcnt(16)
	v_pk_fma_f32 v[168:169], v[124:125], v[96:97], v[168:169]
	v_pk_fma_f32 v[170:171], v[126:127], v[98:99], v[170:171]
	v_pk_fma_f32 v[172:173], v[120:121], v[100:101], v[172:173]
	v_pk_fma_f32 v[174:175], v[122:123], v[102:103], v[174:175]
	v_pk_mul_f32 v[220:221], v[168:169], v[152:153]
	v_pk_mul_f32 v[222:223], v[170:171], v[154:155]
	v_pk_mul_f32 v[224:225], v[172:173], v[156:157]
	v_pk_mul_f32 v[226:227], v[174:175], v[158:159]
	v_cvt_pk_bf16_f32 v124, v168, v169
	v_cvt_pk_bf16_f32 v125, v170, v171
	v_cvt_pk_bf16_f32 v126, v172, v173
	v_cvt_pk_bf16_f32 v127, v174, v175
	v_cvt_pk_bf16_f32 v120, v220, v221
	v_cvt_pk_bf16_f32 v121, v222, v223
	v_cvt_pk_bf16_f32 v122, v224, v225
	v_cvt_pk_bf16_f32 v123, v226, v227
	s_add_u32 s18, s6, 0x8000
	s_addc_u32 s19, s7, 0
	global_store_dwordx4 v238, v[124:127], s[18:19] offset:0
	s_add_u32 s20, s10, 0x8000
	s_addc_u32 s21, s11, 0
	global_store_dwordx4 v238, v[120:123], s[20:21] offset:0
	v_pk_mul_f32 v[220:221], v[168:169], v[168:169]
	v_pk_mul_f32 v[222:223], v[170:171], v[170:171]
	v_pk_mul_f32 v[224:225], v[172:173], v[172:173]
	v_pk_mul_f32 v[226:227], v[174:175], v[174:175]
	v_add_f32_e32 v220, v220, v221
	v_add_f32_e32 v222, v222, v223
	v_add_f32_e32 v224, v224, v225
	v_add_f32_e32 v226, v226, v227
	v_add_f32_e32 v220, v220, v222
	v_add_f32_e32 v224, v224, v226
	v_add_f32_e32 v241, v220, v224
	s_add_u32 s20, s52, 0xb0000
	s_addc_u32 s21, s53, 0
	global_load_dwordx4 v[168:171], v237, s[20:21] offset:0
	global_load_dwordx4 v[172:175], v237, s[20:21] offset:16
	s_waitcnt vmcnt(18)
	v_pk_fma_f32 v[176:177], v[116:117], v[96:97], v[176:177]
	v_pk_fma_f32 v[178:179], v[118:119], v[98:99], v[178:179]
	v_pk_fma_f32 v[180:181], v[112:113], v[100:101], v[180:181]
	v_pk_fma_f32 v[182:183], v[114:115], v[102:103], v[182:183]
	v_pk_mul_f32 v[220:221], v[176:177], v[152:153]
	v_pk_mul_f32 v[222:223], v[178:179], v[154:155]
	v_pk_mul_f32 v[224:225], v[180:181], v[156:157]
	v_pk_mul_f32 v[226:227], v[182:183], v[158:159]
	v_cvt_pk_bf16_f32 v116, v176, v177
	v_cvt_pk_bf16_f32 v117, v178, v179
	v_cvt_pk_bf16_f32 v118, v180, v181
	v_cvt_pk_bf16_f32 v119, v182, v183
	v_cvt_pk_bf16_f32 v112, v220, v221
	v_cvt_pk_bf16_f32 v113, v222, v223
	v_cvt_pk_bf16_f32 v114, v224, v225
	v_cvt_pk_bf16_f32 v115, v226, v227
	s_add_u32 s18, s6, 0x10000
	s_addc_u32 s19, s7, 0
	global_store_dwordx4 v238, v[116:119], s[18:19] offset:0
	s_add_u32 s20, s10, 0x10000
	s_addc_u32 s21, s11, 0
	global_store_dwordx4 v238, v[112:115], s[20:21] offset:0
	v_pk_mul_f32 v[220:221], v[176:177], v[176:177]
	v_pk_mul_f32 v[222:223], v[178:179], v[178:179]
	v_pk_mul_f32 v[224:225], v[180:181], v[180:181]
	v_pk_mul_f32 v[226:227], v[182:183], v[182:183]
	v_add_f32_e32 v220, v220, v221
	v_add_f32_e32 v222, v222, v223
	v_add_f32_e32 v224, v224, v225
	v_add_f32_e32 v226, v226, v227
	v_add_f32_e32 v220, v220, v222
	v_add_f32_e32 v224, v224, v226
	v_add_f32_e32 v242, v220, v224
	s_add_u32 s20, s52, 0x0
	s_addc_u32 s21, s53, 0
	global_load_dwordx4 v[124:127], v237, s[20:21] offset:512
	global_load_dwordx4 v[120:123], v237, s[20:21] offset:528
	s_waitcnt vmcnt(20)
	v_pk_fma_f32 v[184:185], v[108:109], v[96:97], v[184:185]
	v_pk_fma_f32 v[186:187], v[110:111], v[98:99], v[186:187]
	v_pk_fma_f32 v[188:189], v[104:105], v[100:101], v[188:189]
	v_pk_fma_f32 v[190:191], v[106:107], v[102:103], v[190:191]
	v_pk_mul_f32 v[220:221], v[184:185], v[152:153]
	v_pk_mul_f32 v[222:223], v[186:187], v[154:155]
	v_pk_mul_f32 v[224:225], v[188:189], v[156:157]
	v_pk_mul_f32 v[226:227], v[190:191], v[158:159]
	v_cvt_pk_bf16_f32 v108, v184, v185
	v_cvt_pk_bf16_f32 v109, v186, v187
	v_cvt_pk_bf16_f32 v110, v188, v189
	v_cvt_pk_bf16_f32 v111, v190, v191
	v_cvt_pk_bf16_f32 v104, v220, v221
	v_cvt_pk_bf16_f32 v105, v222, v223
	v_cvt_pk_bf16_f32 v106, v224, v225
	v_cvt_pk_bf16_f32 v107, v226, v227
	s_add_u32 s18, s6, 0x18000
	s_addc_u32 s19, s7, 0
	global_store_dwordx4 v238, v[108:111], s[18:19] offset:0
	s_add_u32 s20, s10, 0x18000
	s_addc_u32 s21, s11, 0
	global_store_dwordx4 v238, v[104:107], s[20:21] offset:0
	v_pk_mul_f32 v[220:221], v[184:185], v[184:185]
	v_pk_mul_f32 v[222:223], v[186:187], v[186:187]
	v_pk_mul_f32 v[224:225], v[188:189], v[188:189]
	v_pk_mul_f32 v[226:227], v[190:191], v[190:191]
	v_add_f32_e32 v220, v220, v221
	v_add_f32_e32 v222, v222, v223
	v_add_f32_e32 v224, v224, v225
	v_add_f32_e32 v226, v226, v227
	v_add_f32_e32 v220, v220, v222
	v_add_f32_e32 v224, v224, v226
	v_add_f32_e32 v243, v220, v224
	s_add_u32 s20, s52, 0x10000
	s_addc_u32 s21, s53, 0
	global_load_dwordx4 v[176:179], v237, s[20:21] offset:512
	global_load_dwordx4 v[180:183], v237, s[20:21] offset:528
	s_waitcnt vmcnt(22)
	v_pk_fma_f32 v[192:193], v[92:93], v[96:97], v[192:193]
	v_pk_fma_f32 v[194:195], v[94:95], v[98:99], v[194:195]
	v_pk_fma_f32 v[196:197], v[88:89], v[100:101], v[196:197]
	v_pk_fma_f32 v[198:199], v[90:91], v[102:103], v[198:199]
	v_pk_mul_f32 v[220:221], v[192:193], v[152:153]
	v_pk_mul_f32 v[222:223], v[194:195], v[154:155]
	v_pk_mul_f32 v[224:225], v[196:197], v[156:157]
	v_pk_mul_f32 v[226:227], v[198:199], v[158:159]
	v_cvt_pk_bf16_f32 v92, v192, v193
	v_cvt_pk_bf16_f32 v93, v194, v195
	v_cvt_pk_bf16_f32 v94, v196, v197
	v_cvt_pk_bf16_f32 v95, v198, v199
	v_cvt_pk_bf16_f32 v88, v220, v221
	v_cvt_pk_bf16_f32 v89, v222, v223
	v_cvt_pk_bf16_f32 v90, v224, v225
	v_cvt_pk_bf16_f32 v91, v226, v227
	s_add_u32 s18, s6, 0x40000
	s_addc_u32 s19, s7, 0
	global_store_dwordx4 v238, v[92:95], s[18:19] offset:0
	s_add_u32 s20, s10, 0x40000
	s_addc_u32 s21, s11, 0
	global_store_dwordx4 v238, v[88:91], s[20:21] offset:0
	v_pk_mul_f32 v[220:221], v[192:193], v[192:193]
	v_pk_mul_f32 v[222:223], v[194:195], v[194:195]
	v_pk_mul_f32 v[224:225], v[196:197], v[196:197]
	v_pk_mul_f32 v[226:227], v[198:199], v[198:199]
	v_add_f32_e32 v220, v220, v221
	v_add_f32_e32 v222, v222, v223
	v_add_f32_e32 v224, v224, v225
	v_add_f32_e32 v226, v226, v227
	v_add_f32_e32 v220, v220, v222
	v_add_f32_e32 v224, v224, v226
	v_add_f32_e32 v244, v220, v224
	s_add_u32 s20, s52, 0x20000
	s_addc_u32 s21, s53, 0
	global_load_dwordx4 v[116:119], v237, s[20:21] offset:512
	global_load_dwordx4 v[112:115], v237, s[20:21] offset:528
	s_waitcnt vmcnt(24)
	v_pk_fma_f32 v[200:201], v[84:85], v[96:97], v[200:201]
	v_pk_fma_f32 v[202:203], v[86:87], v[98:99], v[202:203]
	v_pk_fma_f32 v[204:205], v[80:81], v[100:101], v[204:205]
	v_pk_fma_f32 v[206:207], v[82:83], v[102:103], v[206:207]
	v_pk_mul_f32 v[220:221], v[200:201], v[152:153]
	v_pk_mul_f32 v[222:223], v[202:203], v[154:155]
	v_pk_mul_f32 v[224:225], v[204:205], v[156:157]
	v_pk_mul_f32 v[226:227], v[206:207], v[158:159]
	v_cvt_pk_bf16_f32 v84, v200, v201
	v_cvt_pk_bf16_f32 v85, v202, v203
	v_cvt_pk_bf16_f32 v86, v204, v205
	v_cvt_pk_bf16_f32 v87, v206, v207
	v_cvt_pk_bf16_f32 v80, v220, v221
	v_cvt_pk_bf16_f32 v81, v222, v223
	v_cvt_pk_bf16_f32 v82, v224, v225
	v_cvt_pk_bf16_f32 v83, v226, v227
	s_add_u32 s18, s6, 0x48000
	s_addc_u32 s19, s7, 0
	global_store_dwordx4 v238, v[84:87], s[18:19] offset:0
	s_add_u32 s20, s10, 0x48000
	s_addc_u32 s21, s11, 0
	global_store_dwordx4 v238, v[80:83], s[20:21] offset:0
	v_pk_mul_f32 v[220:221], v[200:201], v[200:201]
	v_pk_mul_f32 v[222:223], v[202:203], v[202:203]
	v_pk_mul_f32 v[224:225], v[204:205], v[204:205]
	v_pk_mul_f32 v[226:227], v[206:207], v[206:207]
	v_add_f32_e32 v220, v220, v221
	v_add_f32_e32 v222, v222, v223
	v_add_f32_e32 v224, v224, v225
	v_add_f32_e32 v226, v226, v227
	v_add_f32_e32 v220, v220, v222
	v_add_f32_e32 v224, v224, v226
	v_add_f32_e32 v245, v220, v224
	s_add_u32 s20, s52, 0x30000
	s_addc_u32 s21, s53, 0
	global_load_dwordx4 v[184:187], v237, s[20:21] offset:512
	global_load_dwordx4 v[188:191], v237, s[20:21] offset:528
	s_waitcnt vmcnt(26)
	v_pk_fma_f32 v[208:209], v[76:77], v[96:97], v[208:209]
	v_pk_fma_f32 v[210:211], v[78:79], v[98:99], v[210:211]
	v_pk_fma_f32 v[212:213], v[72:73], v[100:101], v[212:213]
	v_pk_fma_f32 v[214:215], v[74:75], v[102:103], v[214:215]
	v_pk_mul_f32 v[220:221], v[208:209], v[152:153]
	v_pk_mul_f32 v[222:223], v[210:211], v[154:155]
	v_pk_mul_f32 v[224:225], v[212:213], v[156:157]
	v_pk_mul_f32 v[226:227], v[214:215], v[158:159]
	v_cvt_pk_bf16_f32 v76, v208, v209
	v_cvt_pk_bf16_f32 v77, v210, v211
	v_cvt_pk_bf16_f32 v78, v212, v213
	v_cvt_pk_bf16_f32 v79, v214, v215
	v_cvt_pk_bf16_f32 v72, v220, v221
	v_cvt_pk_bf16_f32 v73, v222, v223
	v_cvt_pk_bf16_f32 v74, v224, v225
	v_cvt_pk_bf16_f32 v75, v226, v227
	s_add_u32 s18, s6, 0x50000
	s_addc_u32 s19, s7, 0
	global_store_dwordx4 v238, v[76:79], s[18:19] offset:0
	s_add_u32 s20, s10, 0x50000
	s_addc_u32 s21, s11, 0
	global_store_dwordx4 v238, v[72:75], s[20:21] offset:0
	v_pk_mul_f32 v[220:221], v[208:209], v[208:209]
	v_pk_mul_f32 v[222:223], v[210:211], v[210:211]
	v_pk_mul_f32 v[224:225], v[212:213], v[212:213]
	v_pk_mul_f32 v[226:227], v[214:215], v[214:215]
	v_add_f32_e32 v220, v220, v221
	v_add_f32_e32 v222, v222, v223
	v_add_f32_e32 v224, v224, v225
	v_add_f32_e32 v226, v226, v227
	v_add_f32_e32 v220, v220, v222
	v_add_f32_e32 v224, v224, v226
	v_add_f32_e32 v246, v220, v224
	s_add_u32 s20, s52, 0x80000
	s_addc_u32 s21, s53, 0
	global_load_dwordx4 v[108:111], v237, s[20:21] offset:512
	global_load_dwordx4 v[104:107], v237, s[20:21] offset:528
	s_waitcnt vmcnt(20)
	v_pk_fma_f32 v[168:169], v[68:69], v[96:97], v[168:169]
	v_pk_fma_f32 v[170:171], v[70:71], v[98:99], v[170:171]
	v_pk_fma_f32 v[172:173], v[64:65], v[100:101], v[172:173]
	v_pk_fma_f32 v[174:175], v[66:67], v[102:103], v[174:175]
	v_pk_mul_f32 v[220:221], v[168:169], v[152:153]
	v_pk_mul_f32 v[222:223], v[170:171], v[154:155]
	v_pk_mul_f32 v[224:225], v[172:173], v[156:157]
	v_pk_mul_f32 v[226:227], v[174:175], v[158:159]
	v_cvt_pk_bf16_f32 v68, v168, v169
	v_cvt_pk_bf16_f32 v69, v170, v171
	v_cvt_pk_bf16_f32 v70, v172, v173
	v_cvt_pk_bf16_f32 v71, v174, v175
	v_cvt_pk_bf16_f32 v64, v220, v221
	v_cvt_pk_bf16_f32 v65, v222, v223
	v_cvt_pk_bf16_f32 v66, v224, v225
	v_cvt_pk_bf16_f32 v67, v226, v227
	s_add_u32 s18, s6, 0x58000
	s_addc_u32 s19, s7, 0
	global_store_dwordx4 v238, v[68:71], s[18:19] offset:0
	s_add_u32 s20, s10, 0x58000
	s_addc_u32 s21, s11, 0
	global_store_dwordx4 v238, v[64:67], s[20:21] offset:0
	v_pk_mul_f32 v[220:221], v[168:169], v[168:169]
	v_pk_mul_f32 v[222:223], v[170:171], v[170:171]
	v_pk_mul_f32 v[224:225], v[172:173], v[172:173]
	v_pk_mul_f32 v[226:227], v[174:175], v[174:175]
	v_add_f32_e32 v220, v220, v221
	v_add_f32_e32 v222, v222, v223
	v_add_f32_e32 v224, v224, v225
	v_add_f32_e32 v226, v226, v227
	v_add_f32_e32 v220, v220, v222
	v_add_f32_e32 v224, v224, v226
	v_add_f32_e32 v247, v220, v224
	s_add_u32 s20, s52, 0x90000
	s_addc_u32 s21, s53, 0
	global_load_dwordx4 v[192:195], v237, s[20:21] offset:512
	global_load_dwordx4 v[196:199], v237, s[20:21] offset:528
	s_waitcnt vmcnt(20)
	v_pk_mul_f32 v[160:161], v[160:161], 0.5 op_sel_hi:[1,0]
	v_pk_mul_f32 v[162:163], v[162:163], 0.5 op_sel_hi:[1,0]
	v_pk_mul_f32 v[164:165], v[164:165], 0.5 op_sel_hi:[1,0]
	v_pk_mul_f32 v[166:167], v[166:167], 0.5 op_sel_hi:[1,0]
	v_pk_fma_f32 v[124:125], v[60:61], v[160:161], v[124:125]
	v_pk_fma_f32 v[126:127], v[62:63], v[162:163], v[126:127]
	v_pk_fma_f32 v[120:121], v[56:57], v[164:165], v[120:121]
	v_pk_fma_f32 v[122:123], v[58:59], v[166:167], v[122:123]
	v_pk_mul_f32 v[220:221], v[124:125], v[132:133]
	v_pk_mul_f32 v[222:223], v[126:127], v[134:135]
	v_pk_mul_f32 v[224:225], v[120:121], v[128:129]
	v_pk_mul_f32 v[226:227], v[122:123], v[130:131]
	v_cvt_pk_bf16_f32 v60, v124, v125
	v_cvt_pk_bf16_f32 v61, v126, v127
	v_cvt_pk_bf16_f32 v62, v120, v121
	v_cvt_pk_bf16_f32 v63, v122, v123
	v_cvt_pk_bf16_f32 v56, v220, v221
	v_cvt_pk_bf16_f32 v57, v222, v223
	v_cvt_pk_bf16_f32 v58, v224, v225
	v_cvt_pk_bf16_f32 v59, v226, v227
	s_add_u32 s18, s6, 0x0
	s_addc_u32 s19, s7, 0
	global_store_dwordx4 v238, v[60:63], s[18:19] offset:256
	s_add_u32 s20, s10, 0x0
	s_addc_u32 s21, s11, 0
	global_store_dwordx4 v238, v[56:59], s[20:21] offset:256
	v_pk_mul_f32 v[220:221], v[124:125], v[124:125]
	v_pk_mul_f32 v[222:223], v[126:127], v[126:127]
	v_pk_mul_f32 v[224:225], v[120:121], v[120:121]
	v_pk_mul_f32 v[226:227], v[122:123], v[122:123]
	v_add_f32_e32 v220, v220, v221
	v_add_f32_e32 v222, v222, v223
	v_add_f32_e32 v224, v224, v225
	v_add_f32_e32 v226, v226, v227
	v_add_f32_e32 v220, v220, v222
	v_add_f32_e32 v224, v224, v226
	v_add_f32_e32 v220, v220, v224
	v_add_f32_e32 v240, v240, v220
	s_add_u32 s20, s52, 0xa0000
	s_addc_u32 s21, s53, 0
	global_load_dwordx4 v[92:95], v237, s[20:21] offset:512
	global_load_dwordx4 v[88:91], v237, s[20:21] offset:528
	s_waitcnt vmcnt(20)
	v_pk_fma_f32 v[176:177], v[52:53], v[160:161], v[176:177]
	v_pk_fma_f32 v[178:179], v[54:55], v[162:163], v[178:179]
	v_pk_fma_f32 v[180:181], v[48:49], v[164:165], v[180:181]
	v_pk_fma_f32 v[182:183], v[50:51], v[166:167], v[182:183]
	v_pk_mul_f32 v[220:221], v[176:177], v[132:133]
	v_pk_mul_f32 v[222:223], v[178:179], v[134:135]
	v_pk_mul_f32 v[224:225], v[180:181], v[128:129]
	v_pk_mul_f32 v[226:227], v[182:183], v[130:131]
	v_cvt_pk_bf16_f32 v52, v176, v177
	v_cvt_pk_bf16_f32 v53, v178, v179
	v_cvt_pk_bf16_f32 v54, v180, v181
	v_cvt_pk_bf16_f32 v55, v182, v183
	v_cvt_pk_bf16_f32 v48, v220, v221
	v_cvt_pk_bf16_f32 v49, v222, v223
	v_cvt_pk_bf16_f32 v50, v224, v225
	v_cvt_pk_bf16_f32 v51, v226, v227
	s_add_u32 s18, s6, 0x8000
	s_addc_u32 s19, s7, 0
	global_store_dwordx4 v238, v[52:55], s[18:19] offset:256
	s_add_u32 s20, s10, 0x8000
	s_addc_u32 s21, s11, 0
	global_store_dwordx4 v238, v[48:51], s[20:21] offset:256
	v_pk_mul_f32 v[220:221], v[176:177], v[176:177]
	v_pk_mul_f32 v[222:223], v[178:179], v[178:179]
	v_pk_mul_f32 v[224:225], v[180:181], v[180:181]
	v_pk_mul_f32 v[226:227], v[182:183], v[182:183]
	v_add_f32_e32 v220, v220, v221
	v_add_f32_e32 v222, v222, v223
	v_add_f32_e32 v224, v224, v225
	v_add_f32_e32 v226, v226, v227
	v_add_f32_e32 v220, v220, v222
	v_add_f32_e32 v224, v224, v226
	v_add_f32_e32 v220, v220, v224
	v_add_f32_e32 v241, v241, v220
	s_add_u32 s20, s52, 0xb0000
	s_addc_u32 s21, s53, 0
	global_load_dwordx4 v[200:203], v237, s[20:21] offset:512
	global_load_dwordx4 v[204:207], v237, s[20:21] offset:528
	s_waitcnt vmcnt(20)
	v_pk_fma_f32 v[116:117], v[44:45], v[160:161], v[116:117]
	v_pk_fma_f32 v[118:119], v[46:47], v[162:163], v[118:119]
	v_pk_fma_f32 v[112:113], v[40:41], v[164:165], v[112:113]
	v_pk_fma_f32 v[114:115], v[42:43], v[166:167], v[114:115]
	v_pk_mul_f32 v[220:221], v[116:117], v[132:133]
	v_pk_mul_f32 v[222:223], v[118:119], v[134:135]
	v_pk_mul_f32 v[224:225], v[112:113], v[128:129]
	v_pk_mul_f32 v[226:227], v[114:115], v[130:131]
	v_cvt_pk_bf16_f32 v44, v116, v117
	v_cvt_pk_bf16_f32 v45, v118, v119
	v_cvt_pk_bf16_f32 v46, v112, v113
	v_cvt_pk_bf16_f32 v47, v114, v115
	v_cvt_pk_bf16_f32 v40, v220, v221
	v_cvt_pk_bf16_f32 v41, v222, v223
	v_cvt_pk_bf16_f32 v42, v224, v225
	v_cvt_pk_bf16_f32 v43, v226, v227
	s_add_u32 s18, s6, 0x10000
	s_addc_u32 s19, s7, 0
	global_store_dwordx4 v238, v[44:47], s[18:19] offset:256
	s_add_u32 s20, s10, 0x10000
	s_addc_u32 s21, s11, 0
	global_store_dwordx4 v238, v[40:43], s[20:21] offset:256
	v_pk_mul_f32 v[220:221], v[116:117], v[116:117]
	v_pk_mul_f32 v[222:223], v[118:119], v[118:119]
	v_pk_mul_f32 v[224:225], v[112:113], v[112:113]
	v_pk_mul_f32 v[226:227], v[114:115], v[114:115]
	v_add_f32_e32 v220, v220, v221
	v_add_f32_e32 v222, v222, v223
	v_add_f32_e32 v224, v224, v225
	v_add_f32_e32 v226, v226, v227
	v_add_f32_e32 v220, v220, v222
	v_add_f32_e32 v224, v224, v226
	v_add_f32_e32 v220, v220, v224
	v_add_f32_e32 v242, v242, v220
	s_waitcnt vmcnt(18)
	v_pk_fma_f32 v[184:185], v[36:37], v[160:161], v[184:185]
	v_pk_fma_f32 v[186:187], v[38:39], v[162:163], v[186:187]
	v_pk_fma_f32 v[188:189], v[32:33], v[164:165], v[188:189]
	v_pk_fma_f32 v[190:191], v[34:35], v[166:167], v[190:191]
	v_pk_mul_f32 v[220:221], v[184:185], v[132:133]
	v_pk_mul_f32 v[222:223], v[186:187], v[134:135]
	v_pk_mul_f32 v[224:225], v[188:189], v[128:129]
	v_pk_mul_f32 v[226:227], v[190:191], v[130:131]
	v_cvt_pk_bf16_f32 v36, v184, v185
	v_cvt_pk_bf16_f32 v37, v186, v187
	v_cvt_pk_bf16_f32 v38, v188, v189
	v_cvt_pk_bf16_f32 v39, v190, v191
	v_cvt_pk_bf16_f32 v32, v220, v221
	v_cvt_pk_bf16_f32 v33, v222, v223
	v_cvt_pk_bf16_f32 v34, v224, v225
	v_cvt_pk_bf16_f32 v35, v226, v227
	s_add_u32 s18, s6, 0x18000
	s_addc_u32 s19, s7, 0
	global_store_dwordx4 v238, v[36:39], s[18:19] offset:256
	s_add_u32 s20, s10, 0x18000
	s_addc_u32 s21, s11, 0
	global_store_dwordx4 v238, v[32:35], s[20:21] offset:256
	v_pk_mul_f32 v[220:221], v[184:185], v[184:185]
	v_pk_mul_f32 v[222:223], v[186:187], v[186:187]
	v_pk_mul_f32 v[224:225], v[188:189], v[188:189]
	v_pk_mul_f32 v[226:227], v[190:191], v[190:191]
	v_add_f32_e32 v220, v220, v221
	v_add_f32_e32 v222, v222, v223
	v_add_f32_e32 v224, v224, v225
	v_add_f32_e32 v226, v226, v227
	v_add_f32_e32 v220, v220, v222
	v_add_f32_e32 v224, v224, v226
	v_add_f32_e32 v220, v220, v224
	v_add_f32_e32 v243, v243, v220
	s_waitcnt vmcnt(16)
	v_pk_fma_f32 v[108:109], v[28:29], v[160:161], v[108:109]
	v_pk_fma_f32 v[110:111], v[30:31], v[162:163], v[110:111]
	v_pk_fma_f32 v[104:105], v[24:25], v[164:165], v[104:105]
	v_pk_fma_f32 v[106:107], v[26:27], v[166:167], v[106:107]
	v_pk_mul_f32 v[220:221], v[108:109], v[132:133]
	v_pk_mul_f32 v[222:223], v[110:111], v[134:135]
	v_pk_mul_f32 v[224:225], v[104:105], v[128:129]
	v_pk_mul_f32 v[226:227], v[106:107], v[130:131]
	v_cvt_pk_bf16_f32 v28, v108, v109
	v_cvt_pk_bf16_f32 v29, v110, v111
	v_cvt_pk_bf16_f32 v30, v104, v105
	v_cvt_pk_bf16_f32 v31, v106, v107
	v_cvt_pk_bf16_f32 v24, v220, v221
	v_cvt_pk_bf16_f32 v25, v222, v223
	v_cvt_pk_bf16_f32 v26, v224, v225
	v_cvt_pk_bf16_f32 v27, v226, v227
	s_add_u32 s18, s6, 0x40000
	s_addc_u32 s19, s7, 0
	global_store_dwordx4 v238, v[28:31], s[18:19] offset:256
	s_add_u32 s20, s10, 0x40000
	s_addc_u32 s21, s11, 0
	global_store_dwordx4 v238, v[24:27], s[20:21] offset:256
	v_pk_mul_f32 v[220:221], v[108:109], v[108:109]
	v_pk_mul_f32 v[222:223], v[110:111], v[110:111]
	v_pk_mul_f32 v[224:225], v[104:105], v[104:105]
	v_pk_mul_f32 v[226:227], v[106:107], v[106:107]
	v_add_f32_e32 v220, v220, v221
	v_add_f32_e32 v222, v222, v223
	v_add_f32_e32 v224, v224, v225
	v_add_f32_e32 v226, v226, v227
	v_add_f32_e32 v220, v220, v222
	v_add_f32_e32 v224, v224, v226
	v_add_f32_e32 v220, v220, v224
	v_add_f32_e32 v244, v244, v220
	s_waitcnt vmcnt(14)
	v_pk_fma_f32 v[192:193], v[20:21], v[160:161], v[192:193]
	v_pk_fma_f32 v[194:195], v[22:23], v[162:163], v[194:195]
	v_pk_fma_f32 v[196:197], v[16:17], v[164:165], v[196:197]
	v_pk_fma_f32 v[198:199], v[18:19], v[166:167], v[198:199]
	v_pk_mul_f32 v[220:221], v[192:193], v[132:133]
	v_pk_mul_f32 v[222:223], v[194:195], v[134:135]
	v_pk_mul_f32 v[224:225], v[196:197], v[128:129]
	v_pk_mul_f32 v[226:227], v[198:199], v[130:131]
	v_cvt_pk_bf16_f32 v20, v192, v193
	v_cvt_pk_bf16_f32 v21, v194, v195
	v_cvt_pk_bf16_f32 v22, v196, v197
	v_cvt_pk_bf16_f32 v23, v198, v199
	v_cvt_pk_bf16_f32 v16, v220, v221
	v_cvt_pk_bf16_f32 v17, v222, v223
	v_cvt_pk_bf16_f32 v18, v224, v225
	v_cvt_pk_bf16_f32 v19, v226, v227
	s_add_u32 s18, s6, 0x48000
	s_addc_u32 s19, s7, 0
	global_store_dwordx4 v238, v[20:23], s[18:19] offset:256
	s_add_u32 s20, s10, 0x48000
	s_addc_u32 s21, s11, 0
	global_store_dwordx4 v238, v[16:19], s[20:21] offset:256
	v_pk_mul_f32 v[220:221], v[192:193], v[192:193]
	v_pk_mul_f32 v[222:223], v[194:195], v[194:195]
	v_pk_mul_f32 v[224:225], v[196:197], v[196:197]
	v_pk_mul_f32 v[226:227], v[198:199], v[198:199]
	v_add_f32_e32 v220, v220, v221
	v_add_f32_e32 v222, v222, v223
	v_add_f32_e32 v224, v224, v225
	v_add_f32_e32 v226, v226, v227
	v_add_f32_e32 v220, v220, v222
	v_add_f32_e32 v224, v224, v226
	v_add_f32_e32 v220, v220, v224
	v_add_f32_e32 v245, v245, v220
	s_waitcnt vmcnt(12)
	v_pk_fma_f32 v[92:93], v[12:13], v[160:161], v[92:93]
	v_pk_fma_f32 v[94:95], v[14:15], v[162:163], v[94:95]
	v_pk_fma_f32 v[88:89], v[8:9], v[164:165], v[88:89]
	v_pk_fma_f32 v[90:91], v[10:11], v[166:167], v[90:91]
	v_pk_mul_f32 v[220:221], v[92:93], v[132:133]
	v_pk_mul_f32 v[222:223], v[94:95], v[134:135]
	v_pk_mul_f32 v[224:225], v[88:89], v[128:129]
	v_pk_mul_f32 v[226:227], v[90:91], v[130:131]
	v_cvt_pk_bf16_f32 v12, v92, v93
	v_cvt_pk_bf16_f32 v13, v94, v95
	v_cvt_pk_bf16_f32 v14, v88, v89
	v_cvt_pk_bf16_f32 v15, v90, v91
	v_cvt_pk_bf16_f32 v8, v220, v221
	v_cvt_pk_bf16_f32 v9, v222, v223
	v_cvt_pk_bf16_f32 v10, v224, v225
	v_cvt_pk_bf16_f32 v11, v226, v227
	s_add_u32 s18, s6, 0x50000
	s_addc_u32 s19, s7, 0
	global_store_dwordx4 v238, v[12:15], s[18:19] offset:256
	s_add_u32 s20, s10, 0x50000
	s_addc_u32 s21, s11, 0
	global_store_dwordx4 v238, v[8:11], s[20:21] offset:256
	v_pk_mul_f32 v[220:221], v[92:93], v[92:93]
	v_pk_mul_f32 v[222:223], v[94:95], v[94:95]
	v_pk_mul_f32 v[224:225], v[88:89], v[88:89]
	v_pk_mul_f32 v[226:227], v[90:91], v[90:91]
	v_add_f32_e32 v220, v220, v221
	v_add_f32_e32 v222, v222, v223
	v_add_f32_e32 v224, v224, v225
	v_add_f32_e32 v226, v226, v227
	v_add_f32_e32 v220, v220, v222
	v_add_f32_e32 v224, v224, v226
	v_add_f32_e32 v220, v220, v224
	v_add_f32_e32 v246, v246, v220
	s_waitcnt vmcnt(10)
	v_pk_fma_f32 v[200:201], v[4:5], v[160:161], v[200:201]
	v_pk_fma_f32 v[202:203], v[6:7], v[162:163], v[202:203]
	v_pk_fma_f32 v[204:205], v[0:1], v[164:165], v[204:205]
	v_pk_fma_f32 v[206:207], v[2:3], v[166:167], v[206:207]
	v_pk_mul_f32 v[220:221], v[200:201], v[132:133]
	v_pk_mul_f32 v[222:223], v[202:203], v[134:135]
	v_pk_mul_f32 v[224:225], v[204:205], v[128:129]
	v_pk_mul_f32 v[226:227], v[206:207], v[130:131]
	v_cvt_pk_bf16_f32 v4, v200, v201
	v_cvt_pk_bf16_f32 v5, v202, v203
	v_cvt_pk_bf16_f32 v6, v204, v205
	v_cvt_pk_bf16_f32 v7, v206, v207
	v_cvt_pk_bf16_f32 v0, v220, v221
	v_cvt_pk_bf16_f32 v1, v222, v223
	v_cvt_pk_bf16_f32 v2, v224, v225
	v_cvt_pk_bf16_f32 v3, v226, v227
	s_add_u32 s18, s6, 0x58000
	s_addc_u32 s19, s7, 0
	global_store_dwordx4 v238, v[4:7], s[18:19] offset:256
	s_add_u32 s20, s10, 0x58000
	s_addc_u32 s21, s11, 0
	global_store_dwordx4 v238, v[0:3], s[20:21] offset:256
	v_pk_mul_f32 v[220:221], v[200:201], v[200:201]
	v_pk_mul_f32 v[222:223], v[202:203], v[202:203]
	v_pk_mul_f32 v[224:225], v[204:205], v[204:205]
	v_pk_mul_f32 v[226:227], v[206:207], v[206:207]
	v_add_f32_e32 v220, v220, v221
	v_add_f32_e32 v222, v222, v223
	v_add_f32_e32 v224, v224, v225
	v_add_f32_e32 v226, v226, v227
	v_add_f32_e32 v220, v220, v222
	v_add_f32_e32 v224, v224, v226
	v_add_f32_e32 v220, v220, v224
	v_add_f32_e32 v247, v247, v220
	ds_bpermute_b32 v220, v249, v240
	ds_bpermute_b32 v221, v249, v241
	ds_bpermute_b32 v222, v249, v242
	ds_bpermute_b32 v223, v249, v243
	ds_bpermute_b32 v224, v249, v244
	ds_bpermute_b32 v225, v249, v245
	ds_bpermute_b32 v226, v249, v246
	ds_bpermute_b32 v227, v249, v247
	s_waitcnt lgkmcnt(0)
	v_add_f32_e32 v240, v240, v220
	v_add_f32_e32 v241, v241, v221
	v_add_f32_e32 v242, v242, v222
	v_add_f32_e32 v243, v243, v223
	v_add_f32_e32 v244, v244, v224
	v_add_f32_e32 v245, v245, v225
	v_add_f32_e32 v246, v246, v226
	v_add_f32_e32 v247, v247, v227
	ds_bpermute_b32 v220, v216, v240
	ds_bpermute_b32 v221, v216, v241
	ds_bpermute_b32 v222, v216, v242
	ds_bpermute_b32 v223, v216, v243
	ds_bpermute_b32 v224, v216, v244
	ds_bpermute_b32 v225, v216, v245
	ds_bpermute_b32 v226, v216, v246
	ds_bpermute_b32 v227, v216, v247
	s_lshl_b32 s18, s65, 2
	s_ashr_i32 s19, s18, 31
	s_lshl_b64 s[18:19], s[18:19], 2
	s_add_u32 s18, s59, s18
	s_addc_u32 s19, s60, s19
	s_waitcnt lgkmcnt(0)
	v_add_f32_e32 v240, v240, v220
	v_add_f32_e32 v241, v241, v221
	v_add_f32_e32 v242, v242, v222
	v_add_f32_e32 v243, v243, v223
	v_add_f32_e32 v244, v244, v224
	v_add_f32_e32 v245, v245, v225
	v_add_f32_e32 v246, v246, v226
	v_add_f32_e32 v247, v247, v227
	v_cmp_eq_u32_e32 vcc, 0, v231
	s_and_saveexec_b64 s[20:21], vcc
	global_store_dword v248, v240, s[18:19] offset:0
	global_store_dword v248, v241, s[18:19] offset:1024
	global_store_dword v248, v242, s[18:19] offset:2048
	global_store_dword v248, v243, s[18:19] offset:3072
	s_add_u32 s18, s18, 0x2000
	s_addc_u32 s19, s19, 0
	global_store_dword v248, v244, s[18:19] offset:0
	global_store_dword v248, v245, s[18:19] offset:1024
	global_store_dword v248, v246, s[18:19] offset:2048
	global_store_dword v248, v247, s[18:19] offset:3072

.LBB0_441:
	s_ashr_i32 s21, s20, 31
	s_lshl_b64 s[22:23], s[20:21], 19
	s_add_u32 s22, s17, s22
	s_addc_u32 s23, s38, s23
	s_and_b64 s[24:25], s[2:3], exec
	s_cselect_b32 s21, s23, s31
	s_cselect_b32 s64, s22, s30
	s_ashr_i32 s19, s18, 31
	s_lshl_b64 s[24:25], s[18:19], 19
	s_add_u32 s24, s39, s24
	s_addc_u32 s25, s40, s25
	s_and_b64 s[34:35], s[2:3], exec
	s_cselect_b32 s19, s25, s29
	s_cselect_b32 s65, s24, s28
	s_add_u32 s66, s28, 0x100
	s_addc_u32 s67, s29, 0
	s_add_u32 s28, s30, 0x40080
	s_addc_u32 s29, s31, 0
	s_mov_b32 s72, -2
	v_mov_b64_e32 v[0:1], 0
	v_mov_b64_e32 v[2:3], 0
	v_mov_b64_e32 v[4:5], 0
	v_mov_b64_e32 v[6:7], 0
	v_mov_b64_e32 v[8:9], 0
	v_mov_b64_e32 v[10:11], 0
	v_mov_b64_e32 v[12:13], 0
	v_mov_b64_e32 v[14:15], 0
	v_mov_b64_e32 v[16:17], 0
	v_mov_b64_e32 v[18:19], 0
	v_mov_b64_e32 v[20:21], 0
	v_mov_b64_e32 v[22:23], 0
	v_mov_b64_e32 v[24:25], 0
	v_mov_b64_e32 v[26:27], 0
	v_mov_b64_e32 v[28:29], 0
	v_mov_b64_e32 v[30:31], 0
	v_mov_b64_e32 v[32:33], 0
	v_mov_b64_e32 v[34:35], 0
	v_mov_b64_e32 v[36:37], 0
	v_mov_b64_e32 v[38:39], 0
	v_mov_b64_e32 v[40:41], 0
	v_mov_b64_e32 v[42:43], 0
	v_mov_b64_e32 v[44:45], 0
	v_mov_b64_e32 v[46:47], 0
	v_mov_b64_e32 v[48:49], 0
	v_mov_b64_e32 v[50:51], 0
	v_mov_b64_e32 v[52:53], 0
	v_mov_b64_e32 v[54:55], 0
	v_mov_b64_e32 v[56:57], 0
	v_mov_b64_e32 v[58:59], 0
	v_mov_b64_e32 v[60:61], 0
	v_mov_b64_e32 v[62:63], 0
	v_mov_b64_e32 v[64:65], 0
	v_mov_b64_e32 v[66:67], 0
	v_mov_b64_e32 v[68:69], 0
	v_mov_b64_e32 v[70:71], 0
	v_mov_b64_e32 v[72:73], 0
	v_mov_b64_e32 v[74:75], 0
	v_mov_b64_e32 v[76:77], 0
	v_mov_b64_e32 v[78:79], 0
	v_mov_b64_e32 v[80:81], 0
	v_mov_b64_e32 v[82:83], 0
	v_mov_b64_e32 v[84:85], 0
	v_mov_b64_e32 v[86:87], 0
	v_mov_b64_e32 v[88:89], 0
	v_mov_b64_e32 v[90:91], 0
	v_mov_b64_e32 v[92:93], 0
	v_mov_b64_e32 v[94:95], 0
	v_mov_b64_e32 v[96:97], 0
	v_mov_b64_e32 v[98:99], 0
	v_mov_b64_e32 v[100:101], 0
	v_mov_b64_e32 v[102:103], 0
	v_mov_b64_e32 v[104:105], 0
	v_mov_b64_e32 v[106:107], 0
	v_mov_b64_e32 v[108:109], 0
	v_mov_b64_e32 v[110:111], 0
	v_mov_b64_e32 v[112:113], 0
	v_mov_b64_e32 v[114:115], 0
	v_mov_b64_e32 v[116:117], 0
	v_mov_b64_e32 v[118:119], 0
	v_mov_b64_e32 v[120:121], 0
	v_mov_b64_e32 v[122:123], 0
	v_mov_b64_e32 v[124:125], 0
	v_mov_b64_e32 v[126:127], 0

.LBB0_759:
	s_ashr_i32 s17, s16, 31
	s_lshl_b64 s[18:19], s[16:17], 18
	s_add_u32 s18, s31, s18
	s_addc_u32 s19, s34, s19
	s_and_b64 s[20:21], s[2:3], exec
	s_cselect_b32 s17, s19, s27
	s_cselect_b32 s52, s18, s26
	s_ashr_i32 s15, s14, 31
	s_lshl_b64 s[20:21], s[14:15], 18
	s_add_u32 s20, s35, s20
	s_addc_u32 s21, s38, s21
	s_and_b64 s[28:29], s[2:3], exec
	s_cselect_b32 s15, s21, s25
	s_cselect_b32 s53, s20, s24
	s_add_u32 s54, s24, 0x100
	s_addc_u32 s55, s25, 0
	s_add_u32 s24, s26, 0x20080
	s_addc_u32 s25, s27, 0
	s_mov_b32 s56, -2
	v_mov_b64_e32 v[0:1], 0
	v_mov_b64_e32 v[2:3], 0
	v_mov_b64_e32 v[4:5], 0
	v_mov_b64_e32 v[6:7], 0
	v_mov_b64_e32 v[8:9], 0
	v_mov_b64_e32 v[10:11], 0
	v_mov_b64_e32 v[12:13], 0
	v_mov_b64_e32 v[14:15], 0
	v_mov_b64_e32 v[16:17], 0
	v_mov_b64_e32 v[18:19], 0
	v_mov_b64_e32 v[20:21], 0
	v_mov_b64_e32 v[22:23], 0
	v_mov_b64_e32 v[24:25], 0
	v_mov_b64_e32 v[26:27], 0
	v_mov_b64_e32 v[28:29], 0
	v_mov_b64_e32 v[30:31], 0
	v_mov_b64_e32 v[32:33], 0
	v_mov_b64_e32 v[34:35], 0
	v_mov_b64_e32 v[36:37], 0
	v_mov_b64_e32 v[38:39], 0
	v_mov_b64_e32 v[40:41], 0
	v_mov_b64_e32 v[42:43], 0
	v_mov_b64_e32 v[44:45], 0
	v_mov_b64_e32 v[46:47], 0
	v_mov_b64_e32 v[48:49], 0
	v_mov_b64_e32 v[50:51], 0
	v_mov_b64_e32 v[52:53], 0
	v_mov_b64_e32 v[54:55], 0
	v_mov_b64_e32 v[56:57], 0
	v_mov_b64_e32 v[58:59], 0
	v_mov_b64_e32 v[60:61], 0
	v_mov_b64_e32 v[62:63], 0
	v_mov_b64_e32 v[64:65], 0
	v_mov_b64_e32 v[66:67], 0
	v_mov_b64_e32 v[68:69], 0
	v_mov_b64_e32 v[70:71], 0
	v_mov_b64_e32 v[72:73], 0
	v_mov_b64_e32 v[74:75], 0
	v_mov_b64_e32 v[76:77], 0
	v_mov_b64_e32 v[78:79], 0
	v_mov_b64_e32 v[80:81], 0
	v_mov_b64_e32 v[82:83], 0
	v_mov_b64_e32 v[84:85], 0
	v_mov_b64_e32 v[86:87], 0
	v_mov_b64_e32 v[88:89], 0
	v_mov_b64_e32 v[90:91], 0
	v_mov_b64_e32 v[92:93], 0
	v_mov_b64_e32 v[94:95], 0
	v_mov_b64_e32 v[96:97], 0
	v_mov_b64_e32 v[98:99], 0
	v_mov_b64_e32 v[100:101], 0
	v_mov_b64_e32 v[102:103], 0
	v_mov_b64_e32 v[104:105], 0
	v_mov_b64_e32 v[106:107], 0
	v_mov_b64_e32 v[108:109], 0
	v_mov_b64_e32 v[110:111], 0
	v_mov_b64_e32 v[112:113], 0
	v_mov_b64_e32 v[114:115], 0
	v_mov_b64_e32 v[116:117], 0
	v_mov_b64_e32 v[118:119], 0
	v_mov_b64_e32 v[120:121], 0
	v_mov_b64_e32 v[122:123], 0
	v_mov_b64_e32 v[124:125], 0
	v_mov_b64_e32 v[126:127], 0

.LBB0_929:
	s_ashr_i32 s27, s26, 31
	s_lshl_b64 s[28:29], s[26:27], 19
	s_add_u32 s28, s21, s28
	s_addc_u32 s29, s23, s29
	s_and_b64 s[30:31], s[2:3], exec
	s_cselect_b32 s27, s29, s35
	s_cselect_b32 s60, s28, s34
	s_ashr_i32 s25, s24, 31
	s_lshl_b64 s[30:31], s[24:25], 19
	s_add_u32 s30, s38, s30
	s_addc_u32 s31, s39, s31
	s_and_b64 s[36:37], s[2:3], exec
	s_cselect_b32 s25, s31, s7
	s_cselect_b32 s61, s30, s6
	s_add_u32 s62, s6, 0x100
	s_addc_u32 s63, s7, 0
	s_add_u32 s6, s34, 0x40080
	s_addc_u32 s7, s35, 0
	s_mov_b32 s64, -2
	v_mov_b64_e32 v[0:1], 0
	v_mov_b64_e32 v[2:3], 0
	v_mov_b64_e32 v[4:5], 0
	v_mov_b64_e32 v[6:7], 0
	v_mov_b64_e32 v[8:9], 0
	v_mov_b64_e32 v[10:11], 0
	v_mov_b64_e32 v[12:13], 0
	v_mov_b64_e32 v[14:15], 0
	v_mov_b64_e32 v[16:17], 0
	v_mov_b64_e32 v[18:19], 0
	v_mov_b64_e32 v[20:21], 0
	v_mov_b64_e32 v[22:23], 0
	v_mov_b64_e32 v[24:25], 0
	v_mov_b64_e32 v[26:27], 0
	v_mov_b64_e32 v[28:29], 0
	v_mov_b64_e32 v[30:31], 0
	v_mov_b64_e32 v[32:33], 0
	v_mov_b64_e32 v[34:35], 0
	v_mov_b64_e32 v[36:37], 0
	v_mov_b64_e32 v[38:39], 0
	v_mov_b64_e32 v[40:41], 0
	v_mov_b64_e32 v[42:43], 0
	v_mov_b64_e32 v[44:45], 0
	v_mov_b64_e32 v[46:47], 0
	v_mov_b64_e32 v[48:49], 0
	v_mov_b64_e32 v[50:51], 0
	v_mov_b64_e32 v[52:53], 0
	v_mov_b64_e32 v[54:55], 0
	v_mov_b64_e32 v[56:57], 0
	v_mov_b64_e32 v[58:59], 0
	v_mov_b64_e32 v[60:61], 0
	v_mov_b64_e32 v[62:63], 0
	v_mov_b64_e32 v[64:65], 0
	v_mov_b64_e32 v[66:67], 0
	v_mov_b64_e32 v[68:69], 0
	v_mov_b64_e32 v[70:71], 0
	v_mov_b64_e32 v[72:73], 0
	v_mov_b64_e32 v[74:75], 0
	v_mov_b64_e32 v[76:77], 0
	v_mov_b64_e32 v[78:79], 0
	v_mov_b64_e32 v[80:81], 0
	v_mov_b64_e32 v[82:83], 0
	v_mov_b64_e32 v[84:85], 0
	v_mov_b64_e32 v[86:87], 0
	v_mov_b64_e32 v[88:89], 0
	v_mov_b64_e32 v[90:91], 0
	v_mov_b64_e32 v[92:93], 0
	v_mov_b64_e32 v[94:95], 0
	v_mov_b64_e32 v[96:97], 0
	v_mov_b64_e32 v[98:99], 0
	v_mov_b64_e32 v[100:101], 0
	v_mov_b64_e32 v[102:103], 0
	v_mov_b64_e32 v[104:105], 0
	v_mov_b64_e32 v[106:107], 0
	v_mov_b64_e32 v[108:109], 0
	v_mov_b64_e32 v[110:111], 0
	v_mov_b64_e32 v[112:113], 0
	v_mov_b64_e32 v[114:115], 0
	v_mov_b64_e32 v[116:117], 0
	v_mov_b64_e32 v[118:119], 0
	v_mov_b64_e32 v[120:121], 0
	v_mov_b64_e32 v[122:123], 0
	v_mov_b64_e32 v[124:125], 0
	v_mov_b64_e32 v[126:127], 0

.LBB0_933:
	v_mov_b32_e32 v128, v157
	v_mov_b32_e32 v130, v163
	s_lshl_b32 s6, s4, 8
	s_add_i32 s6, s6, s51
	v_add_u32_e32 v180, s6, v128
	v_lshlrev_b32_e32 v128, 2, v130
	v_ashrrev_i32_e32 v129, 31, v128
	v_ashrrev_i32_e32 v181, 31, v180
	v_lshl_add_u64 v[160:161], v[128:129], 2, s[12:13]
	v_lshlrev_b64 v[128:129], 6, v[180:181]
	v_add_u32_e32 v174, 16, v180
	v_lshl_add_u64 v[128:129], v[160:161], 0, v[128:129]
	v_ashrrev_i32_e32 v175, 31, v174
	global_load_dwordx4 v[186:189], v[128:129], off
	v_lshlrev_b64 v[128:129], 6, v[174:175]
	v_lshl_add_u64 v[128:129], v[160:161], 0, v[128:129]
	global_load_dwordx4 v[190:193], v[128:129], off
	v_add_u32_e32 v170, 32, v180
	v_ashrrev_i32_e32 v171, 31, v170
	v_lshlrev_b64 v[128:129], 6, v[170:171]
	v_add_u32_e32 v166, 48, v180
	v_lshl_add_u64 v[128:129], v[160:161], 0, v[128:129]
	v_ashrrev_i32_e32 v167, 31, v166
	global_load_dwordx4 v[194:197], v[128:129], off
	v_lshlrev_b64 v[128:129], 6, v[166:167]
	v_lshl_add_u64 v[128:129], v[160:161], 0, v[128:129]
	global_load_dwordx4 v[198:201], v[128:129], off
	v_and_b32_e32 v129, 64, v185
	s_lshl_b32 s5, s5, 7
	v_xor_b32_e32 v128, 16, v185
	v_add_u32_e32 v129, 64, v129
	v_add_u32_e32 v164, 0x80, v180
	v_xor_b32_e32 v131, 32, v185
	s_or_b32 s5, s5, s52
	v_cmp_lt_i32_e32 vcc, v128, v129
	v_ashrrev_i32_e32 v165, 31, v164
	v_lshl_add_u32 v182, v130, 3, s5
	v_cndmask_b32_e32 v130, v185, v128, vcc
	v_cmp_lt_i32_e32 vcc, v131, v129
	v_add_u32_e32 v158, 0x90, v180
	v_lshlrev_b64 v[128:129], 6, v[164:165]
	v_lshl_add_u64 v[128:129], v[160:161], 0, v[128:129]
	v_ashrrev_i32_e32 v159, 31, v158
	global_load_dwordx4 v[202:205], v[128:129], off
	v_lshlrev_b64 v[128:129], 6, v[158:159]
	v_lshl_add_u64 v[128:129], v[160:161], 0, v[128:129]
	global_load_dwordx4 v[206:209], v[128:129], off
	s_ashr_i32 s4, s4, 5
	s_mul_hi_i32 s6, s4, 0x5800
	s_mulk_i32 s4, 0x5800
	s_add_u32 s4, s49, s4
	s_addc_u32 s5, s50, s6
	v_ashrrev_i32_e32 v183, 31, v182
	v_add_u32_e32 v154, 0xa0, v180
	v_add_u32_e32 v152, 0xb0, v180
	v_lshl_add_u64 v[210:211], v[182:183], 2, s[4:5]
	v_cndmask_b32_e32 v131, v185, v131, vcc
	v_ashrrev_i32_e32 v155, 31, v154
	v_ashrrev_i32_e32 v153, 31, v152
	v_add_co_u32_e32 v222, vcc, s47, v210
	v_lshlrev_b32_e32 v156, 2, v130
	v_lshlrev_b32_e32 v159, 2, v131
	v_lshl_add_u64 v[220:221], v[210:211], 0, s[18:19]
	global_load_dwordx4 v[128:131], v[210:211], off offset:16
	global_load_dwordx4 v[132:135], v[210:211], off
	v_addc_co_u32_e32 v223, vcc, 0, v211, vcc
	v_lshlrev_b64 v[210:211], 6, v[154:155]
	v_lshlrev_b64 v[212:213], 6, v[152:153]
	v_lshl_add_u64 v[210:211], v[160:161], 0, v[210:211]
	v_lshl_add_u64 v[160:161], v[160:161], 0, v[212:213]
	global_load_dwordx4 v[210:213], v[210:211], off
	s_nop 0
	global_load_dwordx4 v[214:217], v[160:161], off
	global_load_dwordx4 v[226:229], v[222:223], off offset:3072
	global_load_dwordx4 v[230:233], v[220:221], off offset:16
	v_mov_b64_e32 v[218:219], s[22:23]
	s_waitcnt vmcnt(0)
	v_mov_b32_e32 v160, v187
	v_mov_b32_e32 v161, v188
	v_mov_b32_e32 v187, v189
	v_pk_add_f32 v[160:161], v[160:161], v[186:187]
	v_mov_b32_e32 v186, v191
	v_mov_b32_e32 v187, v192
	v_mov_b32_e32 v191, v193
	v_pk_add_f32 v[186:187], v[186:187], v[190:191]
	v_mov_b32_e32 v189, v160
	v_mov_b32_e32 v188, v186
	v_mov_b32_e32 v160, v187
	v_pk_add_f32 v[160:161], v[188:189], v[160:161]
	ds_bpermute_b32 v187, v156, v161
	ds_bpermute_b32 v186, v156, v160
	v_mov_b32_e32 v188, v195
	v_mov_b32_e32 v189, v196
	v_mov_b32_e32 v195, v197
	v_mov_b32_e32 v190, v199
	s_waitcnt lgkmcnt(0)
	v_pk_add_f32 v[160:161], v[160:161], v[186:187]
	ds_bpermute_b32 v187, v159, v161
	ds_bpermute_b32 v186, v159, v160
	v_mov_b32_e32 v191, v200
	v_mov_b32_e32 v199, v201
	v_pk_add_f32 v[188:189], v[188:189], v[194:195]
	v_pk_add_f32 v[190:191], v[190:191], v[198:199]
	s_waitcnt lgkmcnt(0)
	v_pk_add_f32 v[160:161], v[160:161], v[186:187]
	v_mov_b32_e32 v186, v190
	v_mov_b32_e32 v187, v188
	v_mov_b32_e32 v188, v191
	v_pk_add_f32 v[186:187], v[186:187], v[188:189]
	ds_bpermute_b32 v189, v156, v187
	ds_bpermute_b32 v188, v156, v186
	v_pk_fma_f32 v[160:161], v[160:161], s[20:21], v[218:219] op_sel_hi:[1,0,0]
	v_mov_b32_e32 v198, v207
	v_mul_f32_e32 v153, 0x4b800000, v161
	v_cmp_gt_f32_e32 vcc, s58, v161
	v_mul_f32_e32 v155, 0x4b800000, v160
	v_cmp_gt_f32_e64 s[4:5], s58, v160
	v_cndmask_b32_e32 v153, v161, v153, vcc
	v_rsq_f32_e32 v153, v153
	v_cndmask_b32_e64 v155, v160, v155, s[4:5]
	s_waitcnt lgkmcnt(0)
	v_pk_add_f32 v[160:161], v[186:187], v[188:189]
	ds_bpermute_b32 v195, v159, v161
	ds_bpermute_b32 v194, v159, v160
	v_mov_b32_e32 v199, v208
	v_mov_b32_e32 v207, v209
	v_pk_add_f32 v[198:199], v[198:199], v[206:207]
	v_mul_f32_e32 v162, 0x45800000, v153
	s_waitcnt lgkmcnt(0)
	v_pk_add_f32 v[160:161], v[160:161], v[194:195]
	v_mov_b32_e32 v194, v203
	v_mov_b32_e32 v195, v204
	v_mov_b32_e32 v203, v205
	v_pk_add_f32 v[194:195], v[194:195], v[202:203]
	v_mov_b32_e32 v200, v198
	v_mov_b32_e32 v201, v194
	v_mov_b32_e32 v194, v199
	v_pk_add_f32 v[194:195], v[200:201], v[194:195]
	v_pk_fma_f32 v[160:161], v[160:161], s[20:21], v[218:219] op_sel_hi:[1,0,0]
	ds_bpermute_b32 v199, v156, v195
	ds_bpermute_b32 v198, v156, v194
	v_cndmask_b32_e32 v196, v153, v162, vcc
	v_mul_f32_e32 v162, 0x4b800000, v161
	v_cmp_gt_f32_e32 vcc, s58, v161
	v_cmp_gt_f32_e64 s[6:7], s58, v160
	v_rsq_f32_e32 v155, v155
	v_cndmask_b32_e32 v161, v161, v162, vcc
	v_rsq_f32_e32 v162, v161
	v_mul_f32_e32 v161, 0x4b800000, v160
	v_cndmask_b32_e64 v160, v160, v161, s[6:7]
	v_rsq_f32_e32 v165, v160
	s_waitcnt lgkmcnt(0)
	v_pk_add_f32 v[160:161], v[194:195], v[198:199]
	ds_bpermute_b32 v195, v159, v161
	ds_bpermute_b32 v194, v159, v160
	v_mov_b32_e32 v198, v215
	v_mov_b32_e32 v199, v216
	v_mov_b32_e32 v215, v217
	v_pk_add_f32 v[198:199], v[198:199], v[214:215]
	s_waitcnt lgkmcnt(0)
	v_pk_add_f32 v[160:161], v[160:161], v[194:195]
	v_mov_b32_e32 v194, v211
	v_mov_b32_e32 v195, v212
	v_mov_b32_e32 v211, v213
	v_pk_add_f32 v[194:195], v[194:195], v[210:211]
	v_mov_b32_e32 v200, v198
	v_mov_b32_e32 v201, v194
	v_mov_b32_e32 v194, v199
	v_pk_add_f32 v[194:195], v[200:201], v[194:195]
	ds_bpermute_b32 v199, v156, v195
	ds_bpermute_b32 v198, v156, v194
	v_mul_f32_e32 v153, 0x45800000, v155
	v_cndmask_b32_e64 v184, v155, v153, s[4:5]
	v_mul_f32_e32 v153, 0x45800000, v162
	v_pk_fma_f32 v[160:161], v[160:161], s[20:21], v[218:219] op_sel_hi:[1,0,0]
	v_cndmask_b32_e32 v178, v162, v153, vcc
	v_mul_f32_e32 v155, 0x4b800000, v161
	v_cmp_gt_f32_e32 vcc, s58, v161
	v_mul_f32_e32 v156, 0x4b800000, v160
	v_cmp_gt_f32_e64 s[4:5], s58, v160
	v_cndmask_b32_e32 v155, v161, v155, vcc
	v_rsq_f32_e32 v155, v155
	v_cndmask_b32_e64 v156, v160, v156, s[4:5]
	s_waitcnt lgkmcnt(0)
	v_pk_add_f32 v[160:161], v[194:195], v[198:199]
	ds_bpermute_b32 v195, v159, v161
	ds_bpermute_b32 v194, v159, v160
	v_mul_f32_e32 v153, 0x45800000, v165
	v_cndmask_b32_e64 v176, v165, v153, s[6:7]
	v_mul_f32_e32 v153, 0x45800000, v155
	v_cndmask_b32_e32 v172, v155, v153, vcc
	s_waitcnt lgkmcnt(0)
	v_pk_add_f32 v[160:161], v[160:161], v[194:195]
	v_rsq_f32_e32 v156, v156
	v_pk_fma_f32 v[160:161], v[160:161], s[20:21], v[218:219] op_sel_hi:[1,0,0]
	v_mul_f32_e32 v155, 0x4b800000, v161
	v_cmp_gt_f32_e32 vcc, s58, v161
	v_mul_f32_e32 v159, 0x4b800000, v160
	v_cmp_gt_f32_e64 s[6:7], s58, v160
	v_cndmask_b32_e32 v155, v161, v155, vcc
	v_rsq_f32_e32 v155, v155
	v_cndmask_b32_e64 v159, v160, v159, s[6:7]
	v_rsq_f32_e32 v159, v159
	v_mul_f32_e32 v153, 0x45800000, v156
	v_cndmask_b32_e64 v168, v156, v153, s[4:5]
	v_mul_f32_e32 v153, 0x45800000, v155
	v_cndmask_b32_e32 v162, v155, v153, vcc
	v_mul_f32_e32 v153, 0x45800000, v159
	v_cndmask_b32_e64 v156, v159, v153, s[6:7]
	s_waitcnt vmcnt(0)
	s_andn2_b64 vcc, exec, s[2:3]
	s_mov_b64 s[2:3], -1
	v_mov_b32_e32 v212, 0xbfb8aa3b
	v_mov_b64_e32 v[208:209], s[10:11]
	v_lshlrev_b64 v[210:211], 1, v[182:183]
	v_pk_fma_f32 v[124:125], v[124:125], v[196:197], v[132:133] op_sel_hi:[1,0,1]
	v_pk_fma_f32 v[126:127], v[126:127], v[196:197], v[134:135] op_sel_hi:[1,0,1]
	v_pk_fma_f32 v[116:117], v[116:117], v[196:197], v[128:129] op_sel_hi:[1,0,1]
	v_pk_fma_f32 v[118:119], v[118:119], v[196:197], v[130:131] op_sel_hi:[1,0,1]
	v_pk_mul_f32 v[198:199], v[124:125], v[212:213] op_sel_hi:[1,0]
	v_pk_mul_f32 v[200:201], v[126:127], v[212:213] op_sel_hi:[1,0]
	v_pk_mul_f32 v[202:203], v[116:117], v[212:213] op_sel_hi:[1,0]
	v_pk_mul_f32 v[204:205], v[118:119], v[212:213] op_sel_hi:[1,0]
	v_exp_f32_e32 v198, v198
	v_exp_f32_e32 v199, v199
	v_exp_f32_e32 v200, v200
	v_exp_f32_e32 v201, v201
	v_exp_f32_e32 v202, v202
	v_exp_f32_e32 v203, v203
	v_exp_f32_e32 v204, v204
	v_exp_f32_e32 v205, v205
	v_pk_fma_f32 v[120:121], v[120:121], v[196:197], v[226:227] op_sel_hi:[1,0,1]
	v_pk_fma_f32 v[122:123], v[122:123], v[196:197], v[228:229] op_sel_hi:[1,0,1]
	v_pk_fma_f32 v[112:113], v[112:113], v[196:197], v[230:231] op_sel_hi:[1,0,1]
	v_pk_fma_f32 v[114:115], v[114:115], v[196:197], v[232:233] op_sel_hi:[1,0,1]
	v_pk_add_f32 v[198:199], v[198:199], 1.0 op_sel_hi:[1,0]
	v_pk_add_f32 v[200:201], v[200:201], 1.0 op_sel_hi:[1,0]
	v_pk_add_f32 v[202:203], v[202:203], 1.0 op_sel_hi:[1,0]
	v_pk_add_f32 v[204:205], v[204:205], 1.0 op_sel_hi:[1,0]
	v_rcp_f32_e32 v198, v198
	v_rcp_f32_e32 v199, v199
	v_rcp_f32_e32 v200, v200
	v_rcp_f32_e32 v201, v201
	v_rcp_f32_e32 v202, v202
	v_rcp_f32_e32 v203, v203
	v_rcp_f32_e32 v204, v204
	v_rcp_f32_e32 v205, v205
	v_mad_i64_i32 v[206:207], s[4:5], v180, s59, v[208:209]
	v_pk_mul_f32 v[124:125], v[124:125], v[198:199]
	v_pk_mul_f32 v[126:127], v[126:127], v[200:201]
	v_pk_mul_f32 v[116:117], v[116:117], v[202:203]
	v_pk_mul_f32 v[118:119], v[118:119], v[204:205]
	v_lshl_add_u64 v[206:207], v[206:207], 0, v[210:211]
	v_pk_mul_f32 v[124:125], v[124:125], v[120:121]
	v_pk_mul_f32 v[126:127], v[126:127], v[122:123]
	v_pk_mul_f32 v[116:117], v[116:117], v[112:113]
	v_pk_mul_f32 v[118:119], v[118:119], v[114:115]
	v_cvt_pk_bf16_f32 v198, v124, v125
	v_cvt_pk_bf16_f32 v199, v126, v127
	v_cvt_pk_bf16_f32 v200, v116, v117
	v_cvt_pk_bf16_f32 v201, v118, v119
	global_store_dwordx4 v[206:207], v[198:201], off
	v_pk_fma_f32 v[108:109], v[108:109], v[184:185], v[132:133] op_sel_hi:[1,0,1]
	v_pk_fma_f32 v[110:111], v[110:111], v[184:185], v[134:135] op_sel_hi:[1,0,1]
	v_pk_fma_f32 v[100:101], v[100:101], v[184:185], v[128:129] op_sel_hi:[1,0,1]
	v_pk_fma_f32 v[102:103], v[102:103], v[184:185], v[130:131] op_sel_hi:[1,0,1]
	v_pk_mul_f32 v[198:199], v[108:109], v[212:213] op_sel_hi:[1,0]
	v_pk_mul_f32 v[200:201], v[110:111], v[212:213] op_sel_hi:[1,0]
	v_pk_mul_f32 v[202:203], v[100:101], v[212:213] op_sel_hi:[1,0]
	v_pk_mul_f32 v[204:205], v[102:103], v[212:213] op_sel_hi:[1,0]
	v_exp_f32_e32 v198, v198
	v_exp_f32_e32 v199, v199
	v_exp_f32_e32 v200, v200
	v_exp_f32_e32 v201, v201
	v_exp_f32_e32 v202, v202
	v_exp_f32_e32 v203, v203
	v_exp_f32_e32 v204, v204
	v_exp_f32_e32 v205, v205
	v_pk_fma_f32 v[104:105], v[104:105], v[184:185], v[226:227] op_sel_hi:[1,0,1]
	v_pk_fma_f32 v[106:107], v[106:107], v[184:185], v[228:229] op_sel_hi:[1,0,1]
	v_pk_fma_f32 v[96:97], v[96:97], v[184:185], v[230:231] op_sel_hi:[1,0,1]
	v_pk_fma_f32 v[98:99], v[98:99], v[184:185], v[232:233] op_sel_hi:[1,0,1]
	v_pk_add_f32 v[198:199], v[198:199], 1.0 op_sel_hi:[1,0]
	v_pk_add_f32 v[200:201], v[200:201], 1.0 op_sel_hi:[1,0]
	v_pk_add_f32 v[202:203], v[202:203], 1.0 op_sel_hi:[1,0]
	v_pk_add_f32 v[204:205], v[204:205], 1.0 op_sel_hi:[1,0]
	v_rcp_f32_e32 v198, v198
	v_rcp_f32_e32 v199, v199
	v_rcp_f32_e32 v200, v200
	v_rcp_f32_e32 v201, v201
	v_rcp_f32_e32 v202, v202
	v_rcp_f32_e32 v203, v203
	v_rcp_f32_e32 v204, v204
	v_rcp_f32_e32 v205, v205
	v_mad_i64_i32 v[206:207], s[4:5], v174, s59, v[208:209]
	v_pk_mul_f32 v[108:109], v[108:109], v[198:199]
	v_pk_mul_f32 v[110:111], v[110:111], v[200:201]
	v_pk_mul_f32 v[100:101], v[100:101], v[202:203]
	v_pk_mul_f32 v[102:103], v[102:103], v[204:205]
	v_lshl_add_u64 v[206:207], v[206:207], 0, v[210:211]
	v_pk_mul_f32 v[108:109], v[108:109], v[104:105]
	v_pk_mul_f32 v[110:111], v[110:111], v[106:107]
	v_pk_mul_f32 v[100:101], v[100:101], v[96:97]
	v_pk_mul_f32 v[102:103], v[102:103], v[98:99]
	v_cvt_pk_bf16_f32 v198, v108, v109
	v_cvt_pk_bf16_f32 v199, v110, v111
	v_cvt_pk_bf16_f32 v200, v100, v101
	v_cvt_pk_bf16_f32 v201, v102, v103
	global_store_dwordx4 v[206:207], v[198:201], off
	v_pk_fma_f32 v[92:93], v[92:93], v[178:179], v[132:133] op_sel_hi:[1,0,1]
	v_pk_fma_f32 v[94:95], v[94:95], v[178:179], v[134:135] op_sel_hi:[1,0,1]
	v_pk_fma_f32 v[84:85], v[84:85], v[178:179], v[128:129] op_sel_hi:[1,0,1]
	v_pk_fma_f32 v[86:87], v[86:87], v[178:179], v[130:131] op_sel_hi:[1,0,1]
	v_pk_mul_f32 v[198:199], v[92:93], v[212:213] op_sel_hi:[1,0]
	v_pk_mul_f32 v[200:201], v[94:95], v[212:213] op_sel_hi:[1,0]
	v_pk_mul_f32 v[202:203], v[84:85], v[212:213] op_sel_hi:[1,0]
	v_pk_mul_f32 v[204:205], v[86:87], v[212:213] op_sel_hi:[1,0]
	v_exp_f32_e32 v198, v198
	v_exp_f32_e32 v199, v199
	v_exp_f32_e32 v200, v200
	v_exp_f32_e32 v201, v201
	v_exp_f32_e32 v202, v202
	v_exp_f32_e32 v203, v203
	v_exp_f32_e32 v204, v204
	v_exp_f32_e32 v205, v205
	v_pk_fma_f32 v[88:89], v[88:89], v[178:179], v[226:227] op_sel_hi:[1,0,1]
	v_pk_fma_f32 v[90:91], v[90:91], v[178:179], v[228:229] op_sel_hi:[1,0,1]
	v_pk_fma_f32 v[80:81], v[80:81], v[178:179], v[230:231] op_sel_hi:[1,0,1]
	v_pk_fma_f32 v[82:83], v[82:83], v[178:179], v[232:233] op_sel_hi:[1,0,1]
	v_pk_add_f32 v[198:199], v[198:199], 1.0 op_sel_hi:[1,0]
	v_pk_add_f32 v[200:201], v[200:201], 1.0 op_sel_hi:[1,0]
	v_pk_add_f32 v[202:203], v[202:203], 1.0 op_sel_hi:[1,0]
	v_pk_add_f32 v[204:205], v[204:205], 1.0 op_sel_hi:[1,0]
	v_rcp_f32_e32 v198, v198
	v_rcp_f32_e32 v199, v199
	v_rcp_f32_e32 v200, v200
	v_rcp_f32_e32 v201, v201
	v_rcp_f32_e32 v202, v202
	v_rcp_f32_e32 v203, v203
	v_rcp_f32_e32 v204, v204
	v_rcp_f32_e32 v205, v205
	v_mad_i64_i32 v[206:207], s[4:5], v170, s59, v[208:209]
	v_pk_mul_f32 v[92:93], v[92:93], v[198:199]
	v_pk_mul_f32 v[94:95], v[94:95], v[200:201]
	v_pk_mul_f32 v[84:85], v[84:85], v[202:203]
	v_pk_mul_f32 v[86:87], v[86:87], v[204:205]
	v_lshl_add_u64 v[206:207], v[206:207], 0, v[210:211]
	v_pk_mul_f32 v[92:93], v[92:93], v[88:89]
	v_pk_mul_f32 v[94:95], v[94:95], v[90:91]
	v_pk_mul_f32 v[84:85], v[84:85], v[80:81]
	v_pk_mul_f32 v[86:87], v[86:87], v[82:83]
	v_cvt_pk_bf16_f32 v198, v92, v93
	v_cvt_pk_bf16_f32 v199, v94, v95
	v_cvt_pk_bf16_f32 v200, v84, v85
	v_cvt_pk_bf16_f32 v201, v86, v87
	global_store_dwordx4 v[206:207], v[198:201], off
	v_pk_fma_f32 v[76:77], v[76:77], v[176:177], v[132:133] op_sel_hi:[1,0,1]
	v_pk_fma_f32 v[78:79], v[78:79], v[176:177], v[134:135] op_sel_hi:[1,0,1]
	v_pk_fma_f32 v[68:69], v[68:69], v[176:177], v[128:129] op_sel_hi:[1,0,1]
	v_pk_fma_f32 v[70:71], v[70:71], v[176:177], v[130:131] op_sel_hi:[1,0,1]
	v_pk_mul_f32 v[198:199], v[76:77], v[212:213] op_sel_hi:[1,0]
	v_pk_mul_f32 v[200:201], v[78:79], v[212:213] op_sel_hi:[1,0]
	v_pk_mul_f32 v[202:203], v[68:69], v[212:213] op_sel_hi:[1,0]
	v_pk_mul_f32 v[204:205], v[70:71], v[212:213] op_sel_hi:[1,0]
	v_exp_f32_e32 v198, v198
	v_exp_f32_e32 v199, v199
	v_exp_f32_e32 v200, v200
	v_exp_f32_e32 v201, v201
	v_exp_f32_e32 v202, v202
	v_exp_f32_e32 v203, v203
	v_exp_f32_e32 v204, v204
	v_exp_f32_e32 v205, v205
	v_pk_fma_f32 v[72:73], v[72:73], v[176:177], v[226:227] op_sel_hi:[1,0,1]
	v_pk_fma_f32 v[74:75], v[74:75], v[176:177], v[228:229] op_sel_hi:[1,0,1]
	v_pk_fma_f32 v[64:65], v[64:65], v[176:177], v[230:231] op_sel_hi:[1,0,1]
	v_pk_fma_f32 v[66:67], v[66:67], v[176:177], v[232:233] op_sel_hi:[1,0,1]
	v_pk_add_f32 v[198:199], v[198:199], 1.0 op_sel_hi:[1,0]
	v_pk_add_f32 v[200:201], v[200:201], 1.0 op_sel_hi:[1,0]
	v_pk_add_f32 v[202:203], v[202:203], 1.0 op_sel_hi:[1,0]
	v_pk_add_f32 v[204:205], v[204:205], 1.0 op_sel_hi:[1,0]
	v_rcp_f32_e32 v198, v198
	v_rcp_f32_e32 v199, v199
	v_rcp_f32_e32 v200, v200
	v_rcp_f32_e32 v201, v201
	v_rcp_f32_e32 v202, v202
	v_rcp_f32_e32 v203, v203
	v_rcp_f32_e32 v204, v204
	v_rcp_f32_e32 v205, v205
	v_mad_i64_i32 v[206:207], s[4:5], v166, s59, v[208:209]
	v_pk_mul_f32 v[76:77], v[76:77], v[198:199]
	v_pk_mul_f32 v[78:79], v[78:79], v[200:201]
	v_pk_mul_f32 v[68:69], v[68:69], v[202:203]
	v_pk_mul_f32 v[70:71], v[70:71], v[204:205]
	v_lshl_add_u64 v[206:207], v[206:207], 0, v[210:211]
	v_pk_mul_f32 v[76:77], v[76:77], v[72:73]
	v_pk_mul_f32 v[78:79], v[78:79], v[74:75]
	v_pk_mul_f32 v[68:69], v[68:69], v[64:65]
	v_pk_mul_f32 v[70:71], v[70:71], v[66:67]
	v_cvt_pk_bf16_f32 v198, v76, v77
	v_cvt_pk_bf16_f32 v199, v78, v79
	v_cvt_pk_bf16_f32 v200, v68, v69
	v_cvt_pk_bf16_f32 v201, v70, v71
	global_store_dwordx4 v[206:207], v[198:201], off
	v_pk_fma_f32 v[60:61], v[60:61], v[172:173], v[132:133] op_sel_hi:[1,0,1]
	v_pk_fma_f32 v[62:63], v[62:63], v[172:173], v[134:135] op_sel_hi:[1,0,1]
	v_pk_fma_f32 v[52:53], v[52:53], v[172:173], v[128:129] op_sel_hi:[1,0,1]
	v_pk_fma_f32 v[54:55], v[54:55], v[172:173], v[130:131] op_sel_hi:[1,0,1]
	v_pk_mul_f32 v[198:199], v[60:61], v[212:213] op_sel_hi:[1,0]
	v_pk_mul_f32 v[200:201], v[62:63], v[212:213] op_sel_hi:[1,0]
	v_pk_mul_f32 v[202:203], v[52:53], v[212:213] op_sel_hi:[1,0]
	v_pk_mul_f32 v[204:205], v[54:55], v[212:213] op_sel_hi:[1,0]
	v_exp_f32_e32 v198, v198
	v_exp_f32_e32 v199, v199
	v_exp_f32_e32 v200, v200
	v_exp_f32_e32 v201, v201
	v_exp_f32_e32 v202, v202
	v_exp_f32_e32 v203, v203
	v_exp_f32_e32 v204, v204
	v_exp_f32_e32 v205, v205
	v_pk_fma_f32 v[56:57], v[56:57], v[172:173], v[226:227] op_sel_hi:[1,0,1]
	v_pk_fma_f32 v[58:59], v[58:59], v[172:173], v[228:229] op_sel_hi:[1,0,1]
	v_pk_fma_f32 v[48:49], v[48:49], v[172:173], v[230:231] op_sel_hi:[1,0,1]
	v_pk_fma_f32 v[50:51], v[50:51], v[172:173], v[232:233] op_sel_hi:[1,0,1]
	v_pk_add_f32 v[198:199], v[198:199], 1.0 op_sel_hi:[1,0]
	v_pk_add_f32 v[200:201], v[200:201], 1.0 op_sel_hi:[1,0]
	v_pk_add_f32 v[202:203], v[202:203], 1.0 op_sel_hi:[1,0]
	v_pk_add_f32 v[204:205], v[204:205], 1.0 op_sel_hi:[1,0]
	v_rcp_f32_e32 v198, v198
	v_rcp_f32_e32 v199, v199
	v_rcp_f32_e32 v200, v200
	v_rcp_f32_e32 v201, v201
	v_rcp_f32_e32 v202, v202
	v_rcp_f32_e32 v203, v203
	v_rcp_f32_e32 v204, v204
	v_rcp_f32_e32 v205, v205
	v_mad_i64_i32 v[206:207], s[4:5], v164, s59, v[208:209]
	v_pk_mul_f32 v[60:61], v[60:61], v[198:199]
	v_pk_mul_f32 v[62:63], v[62:63], v[200:201]
	v_pk_mul_f32 v[52:53], v[52:53], v[202:203]
	v_pk_mul_f32 v[54:55], v[54:55], v[204:205]
	v_lshl_add_u64 v[206:207], v[206:207], 0, v[210:211]
	v_pk_mul_f32 v[60:61], v[60:61], v[56:57]
	v_pk_mul_f32 v[62:63], v[62:63], v[58:59]
	v_pk_mul_f32 v[52:53], v[52:53], v[48:49]
	v_pk_mul_f32 v[54:55], v[54:55], v[50:51]
	v_cvt_pk_bf16_f32 v198, v60, v61
	v_cvt_pk_bf16_f32 v199, v62, v63
	v_cvt_pk_bf16_f32 v200, v52, v53
	v_cvt_pk_bf16_f32 v201, v54, v55
	global_store_dwordx4 v[206:207], v[198:201], off
	v_pk_fma_f32 v[44:45], v[44:45], v[168:169], v[132:133] op_sel_hi:[1,0,1]
	v_pk_fma_f32 v[46:47], v[46:47], v[168:169], v[134:135] op_sel_hi:[1,0,1]
	v_pk_fma_f32 v[36:37], v[36:37], v[168:169], v[128:129] op_sel_hi:[1,0,1]
	v_pk_fma_f32 v[38:39], v[38:39], v[168:169], v[130:131] op_sel_hi:[1,0,1]
	v_pk_mul_f32 v[198:199], v[44:45], v[212:213] op_sel_hi:[1,0]
	v_pk_mul_f32 v[200:201], v[46:47], v[212:213] op_sel_hi:[1,0]
	v_pk_mul_f32 v[202:203], v[36:37], v[212:213] op_sel_hi:[1,0]
	v_pk_mul_f32 v[204:205], v[38:39], v[212:213] op_sel_hi:[1,0]
	v_exp_f32_e32 v198, v198
	v_exp_f32_e32 v199, v199
	v_exp_f32_e32 v200, v200
	v_exp_f32_e32 v201, v201
	v_exp_f32_e32 v202, v202
	v_exp_f32_e32 v203, v203
	v_exp_f32_e32 v204, v204
	v_exp_f32_e32 v205, v205
	v_pk_fma_f32 v[40:41], v[40:41], v[168:169], v[226:227] op_sel_hi:[1,0,1]
	v_pk_fma_f32 v[42:43], v[42:43], v[168:169], v[228:229] op_sel_hi:[1,0,1]
	v_pk_fma_f32 v[32:33], v[32:33], v[168:169], v[230:231] op_sel_hi:[1,0,1]
	v_pk_fma_f32 v[34:35], v[34:35], v[168:169], v[232:233] op_sel_hi:[1,0,1]
	v_pk_add_f32 v[198:199], v[198:199], 1.0 op_sel_hi:[1,0]
	v_pk_add_f32 v[200:201], v[200:201], 1.0 op_sel_hi:[1,0]
	v_pk_add_f32 v[202:203], v[202:203], 1.0 op_sel_hi:[1,0]
	v_pk_add_f32 v[204:205], v[204:205], 1.0 op_sel_hi:[1,0]
	v_rcp_f32_e32 v198, v198
	v_rcp_f32_e32 v199, v199
	v_rcp_f32_e32 v200, v200
	v_rcp_f32_e32 v201, v201
	v_rcp_f32_e32 v202, v202
	v_rcp_f32_e32 v203, v203
	v_rcp_f32_e32 v204, v204
	v_rcp_f32_e32 v205, v205
	v_mad_i64_i32 v[206:207], s[4:5], v158, s59, v[208:209]
	v_pk_mul_f32 v[44:45], v[44:45], v[198:199]
	v_pk_mul_f32 v[46:47], v[46:47], v[200:201]
	v_pk_mul_f32 v[36:37], v[36:37], v[202:203]
	v_pk_mul_f32 v[38:39], v[38:39], v[204:205]
	v_lshl_add_u64 v[206:207], v[206:207], 0, v[210:211]
	v_pk_mul_f32 v[44:45], v[44:45], v[40:41]
	v_pk_mul_f32 v[46:47], v[46:47], v[42:43]
	v_pk_mul_f32 v[36:37], v[36:37], v[32:33]
	v_pk_mul_f32 v[38:39], v[38:39], v[34:35]
	v_cvt_pk_bf16_f32 v198, v44, v45
	v_cvt_pk_bf16_f32 v199, v46, v47
	v_cvt_pk_bf16_f32 v200, v36, v37
	v_cvt_pk_bf16_f32 v201, v38, v39
	global_store_dwordx4 v[206:207], v[198:201], off
	v_pk_fma_f32 v[28:29], v[28:29], v[162:163], v[132:133] op_sel_hi:[1,0,1]
	v_pk_fma_f32 v[30:31], v[30:31], v[162:163], v[134:135] op_sel_hi:[1,0,1]
	v_pk_fma_f32 v[20:21], v[20:21], v[162:163], v[128:129] op_sel_hi:[1,0,1]
	v_pk_fma_f32 v[22:23], v[22:23], v[162:163], v[130:131] op_sel_hi:[1,0,1]
	v_pk_mul_f32 v[198:199], v[28:29], v[212:213] op_sel_hi:[1,0]
	v_pk_mul_f32 v[200:201], v[30:31], v[212:213] op_sel_hi:[1,0]
	v_pk_mul_f32 v[202:203], v[20:21], v[212:213] op_sel_hi:[1,0]
	v_pk_mul_f32 v[204:205], v[22:23], v[212:213] op_sel_hi:[1,0]
	v_exp_f32_e32 v198, v198
	v_exp_f32_e32 v199, v199
	v_exp_f32_e32 v200, v200
	v_exp_f32_e32 v201, v201
	v_exp_f32_e32 v202, v202
	v_exp_f32_e32 v203, v203
	v_exp_f32_e32 v204, v204
	v_exp_f32_e32 v205, v205
	v_pk_fma_f32 v[24:25], v[24:25], v[162:163], v[226:227] op_sel_hi:[1,0,1]
	v_pk_fma_f32 v[26:27], v[26:27], v[162:163], v[228:229] op_sel_hi:[1,0,1]
	v_pk_fma_f32 v[16:17], v[16:17], v[162:163], v[230:231] op_sel_hi:[1,0,1]
	v_pk_fma_f32 v[18:19], v[18:19], v[162:163], v[232:233] op_sel_hi:[1,0,1]
	v_pk_add_f32 v[198:199], v[198:199], 1.0 op_sel_hi:[1,0]
	v_pk_add_f32 v[200:201], v[200:201], 1.0 op_sel_hi:[1,0]
	v_pk_add_f32 v[202:203], v[202:203], 1.0 op_sel_hi:[1,0]
	v_pk_add_f32 v[204:205], v[204:205], 1.0 op_sel_hi:[1,0]
	v_rcp_f32_e32 v198, v198
	v_rcp_f32_e32 v199, v199
	v_rcp_f32_e32 v200, v200
	v_rcp_f32_e32 v201, v201
	v_rcp_f32_e32 v202, v202
	v_rcp_f32_e32 v203, v203
	v_rcp_f32_e32 v204, v204
	v_rcp_f32_e32 v205, v205
	v_mad_i64_i32 v[206:207], s[4:5], v154, s59, v[208:209]
	v_pk_mul_f32 v[28:29], v[28:29], v[198:199]
	v_pk_mul_f32 v[30:31], v[30:31], v[200:201]
	v_pk_mul_f32 v[20:21], v[20:21], v[202:203]
	v_pk_mul_f32 v[22:23], v[22:23], v[204:205]
	v_lshl_add_u64 v[206:207], v[206:207], 0, v[210:211]
	v_pk_mul_f32 v[28:29], v[28:29], v[24:25]
	v_pk_mul_f32 v[30:31], v[30:31], v[26:27]
	v_pk_mul_f32 v[20:21], v[20:21], v[16:17]
	v_pk_mul_f32 v[22:23], v[22:23], v[18:19]
	v_cvt_pk_bf16_f32 v198, v28, v29
	v_cvt_pk_bf16_f32 v199, v30, v31
	v_cvt_pk_bf16_f32 v200, v20, v21
	v_cvt_pk_bf16_f32 v201, v22, v23
	global_store_dwordx4 v[206:207], v[198:201], off
	v_pk_fma_f32 v[12:13], v[12:13], v[156:157], v[132:133] op_sel_hi:[1,0,1]
	v_pk_fma_f32 v[14:15], v[14:15], v[156:157], v[134:135] op_sel_hi:[1,0,1]
	v_pk_fma_f32 v[4:5], v[4:5], v[156:157], v[128:129] op_sel_hi:[1,0,1]
	v_pk_fma_f32 v[6:7], v[6:7], v[156:157], v[130:131] op_sel_hi:[1,0,1]
	v_pk_mul_f32 v[198:199], v[12:13], v[212:213] op_sel_hi:[1,0]
	v_pk_mul_f32 v[200:201], v[14:15], v[212:213] op_sel_hi:[1,0]
	v_pk_mul_f32 v[202:203], v[4:5], v[212:213] op_sel_hi:[1,0]
	v_pk_mul_f32 v[204:205], v[6:7], v[212:213] op_sel_hi:[1,0]
	v_exp_f32_e32 v198, v198
	v_exp_f32_e32 v199, v199
	v_exp_f32_e32 v200, v200
	v_exp_f32_e32 v201, v201
	v_exp_f32_e32 v202, v202
	v_exp_f32_e32 v203, v203
	v_exp_f32_e32 v204, v204
	v_exp_f32_e32 v205, v205
	v_pk_fma_f32 v[8:9], v[8:9], v[156:157], v[226:227] op_sel_hi:[1,0,1]
	v_pk_fma_f32 v[10:11], v[10:11], v[156:157], v[228:229] op_sel_hi:[1,0,1]
	v_pk_fma_f32 v[0:1], v[0:1], v[156:157], v[230:231] op_sel_hi:[1,0,1]
	v_pk_fma_f32 v[2:3], v[2:3], v[156:157], v[232:233] op_sel_hi:[1,0,1]
	v_pk_add_f32 v[198:199], v[198:199], 1.0 op_sel_hi:[1,0]
	v_pk_add_f32 v[200:201], v[200:201], 1.0 op_sel_hi:[1,0]
	v_pk_add_f32 v[202:203], v[202:203], 1.0 op_sel_hi:[1,0]
	v_pk_add_f32 v[204:205], v[204:205], 1.0 op_sel_hi:[1,0]
	v_rcp_f32_e32 v198, v198
	v_rcp_f32_e32 v199, v199
	v_rcp_f32_e32 v200, v200
	v_rcp_f32_e32 v201, v201
	v_rcp_f32_e32 v202, v202
	v_rcp_f32_e32 v203, v203
	v_rcp_f32_e32 v204, v204
	v_rcp_f32_e32 v205, v205
	v_mad_i64_i32 v[206:207], s[4:5], v152, s59, v[208:209]
	v_pk_mul_f32 v[12:13], v[12:13], v[198:199]
	v_pk_mul_f32 v[14:15], v[14:15], v[200:201]
	v_pk_mul_f32 v[4:5], v[4:5], v[202:203]
	v_pk_mul_f32 v[6:7], v[6:7], v[204:205]
	v_lshl_add_u64 v[206:207], v[206:207], 0, v[210:211]
	v_pk_mul_f32 v[12:13], v[12:13], v[8:9]
	v_pk_mul_f32 v[14:15], v[14:15], v[10:11]
	v_pk_mul_f32 v[4:5], v[4:5], v[0:1]
	v_pk_mul_f32 v[6:7], v[6:7], v[2:3]
	v_cvt_pk_bf16_f32 v198, v12, v13
	v_cvt_pk_bf16_f32 v199, v14, v15
	v_cvt_pk_bf16_f32 v200, v4, v5
	v_cvt_pk_bf16_f32 v201, v6, v7
	global_store_dwordx4 v[206:207], v[198:201], off
	s_cbranch_vccnz .LBB0_926
	s_andn2_b64 vcc, exec, s[8:9]
	s_cbranch_vccnz .LBB0_925
	s_barrier
	s_branch .LBB0_925

.LBB0_1001:
	s_add_u32 s48, s16, 0x100
	s_addc_u32 s49, s17, 0
	s_mov_b32 s50, -2
	v_mov_b64_e32 v[0:1], 0
	v_mov_b64_e32 v[2:3], 0
	v_mov_b64_e32 v[4:5], 0
	v_mov_b64_e32 v[6:7], 0
	v_mov_b64_e32 v[8:9], 0
	v_mov_b64_e32 v[10:11], 0
	v_mov_b64_e32 v[12:13], 0
	v_mov_b64_e32 v[14:15], 0
	v_mov_b64_e32 v[16:17], 0
	v_mov_b64_e32 v[18:19], 0
	v_mov_b64_e32 v[20:21], 0
	v_mov_b64_e32 v[22:23], 0
	v_mov_b64_e32 v[24:25], 0
	v_mov_b64_e32 v[26:27], 0
	v_mov_b64_e32 v[28:29], 0
	v_mov_b64_e32 v[30:31], 0
	v_mov_b64_e32 v[32:33], 0
	v_mov_b64_e32 v[34:35], 0
	v_mov_b64_e32 v[36:37], 0
	v_mov_b64_e32 v[38:39], 0
	v_mov_b64_e32 v[40:41], 0
	v_mov_b64_e32 v[42:43], 0
	v_mov_b64_e32 v[44:45], 0
	v_mov_b64_e32 v[46:47], 0
	v_mov_b64_e32 v[48:49], 0
	v_mov_b64_e32 v[50:51], 0
	v_mov_b64_e32 v[52:53], 0
	v_mov_b64_e32 v[54:55], 0
	v_mov_b64_e32 v[56:57], 0
	v_mov_b64_e32 v[58:59], 0
	v_mov_b64_e32 v[60:61], 0
	v_mov_b64_e32 v[62:63], 0
	v_mov_b64_e32 v[64:65], 0
	v_mov_b64_e32 v[66:67], 0
	v_mov_b64_e32 v[68:69], 0
	v_mov_b64_e32 v[70:71], 0
	v_mov_b64_e32 v[72:73], 0
	v_mov_b64_e32 v[74:75], 0
	v_mov_b64_e32 v[76:77], 0
	v_mov_b64_e32 v[78:79], 0
	v_mov_b64_e32 v[80:81], 0
	v_mov_b64_e32 v[82:83], 0
	v_mov_b64_e32 v[84:85], 0
	v_mov_b64_e32 v[86:87], 0
	v_mov_b64_e32 v[88:89], 0
	v_mov_b64_e32 v[90:91], 0
	v_mov_b64_e32 v[92:93], 0
	v_mov_b64_e32 v[94:95], 0
	v_mov_b64_e32 v[96:97], 0
	v_mov_b64_e32 v[98:99], 0
	v_mov_b64_e32 v[100:101], 0
	v_mov_b64_e32 v[102:103], 0
	v_mov_b64_e32 v[104:105], 0
	v_mov_b64_e32 v[106:107], 0
	v_mov_b64_e32 v[108:109], 0
	v_mov_b64_e32 v[110:111], 0
	v_mov_b64_e32 v[112:113], 0
	v_mov_b64_e32 v[114:115], 0
	v_mov_b64_e32 v[116:117], 0
	v_mov_b64_e32 v[118:119], 0
	v_mov_b64_e32 v[120:121], 0
	v_mov_b64_e32 v[122:123], 0
	v_mov_b64_e32 v[124:125], 0
	v_mov_b64_e32 v[126:127], 0
